# v104 with s_setprio 1 raised before the first LDS-DMA issue of each K-loop load phase
# speedup vs baseline: 1.0061x; 1.0007x over previous
.LBB0_333:
	s_add_u32 s68, s56, s49
	s_addc_u32 s70, s57, 0
	s_add_u32 s64, s68, 0x100
	s_addc_u32 s65, s70, 0
	s_and_b64 s[62:63], s[60:61], exec
	s_cselect_b32 s65, s18, s65
	s_cselect_b32 s64, s19, s64
	s_add_u32 s49, s54, s49
	s_addc_u32 s62, s55, 0
	s_add_u32 s49, s49, 0x100
	s_addc_u32 s62, s62, 0
	s_add_i32 s80, 0, 0x10000
	s_and_b64 s[60:61], s[60:61], exec
	s_cselect_b32 s67, s33, s62
	s_cselect_b32 s66, s45, s49
	s_add_i32 s61, 0, 0x14000
	s_add_u32 s72, s68, 0x10080
	s_addc_u32 s73, s70, 0
	s_add_i32 s79, s80, s2
	s_add_i32 m0, s4, 0xc000
	s_add_i32 s82, s4, 0xe000
	s_add_i32 s76, s79, 0x2000
	s_add_u32 s70, s66, 0x10000
	v_add_u32_e32 v152, s80, v138
	v_add_u32_e32 v168, s61, v138
	s_addc_u32 s71, s67, 0
	s_add_i32 s78, s61, s2
	ds_read_b128 v[140:143], v152
	ds_read_b128 v[144:147], v152 offset:1024
	ds_read_b128 v[148:151], v152 offset:2048
	ds_read_b128 v[152:155], v152 offset:3072
	ds_read_b128 v[156:159], v168
	ds_read_b128 v[160:163], v168 offset:1024
	ds_read_b128 v[164:167], v168 offset:2048
	ds_read_b128 v[168:171], v168 offset:3072
	s_add_i32 s77, s78, 0x2000
	s_add_i32 s75, 0, 0x18000
	s_add_i32 s74, 0, 0x1c000
	s_add_u32 s62, s64, 0x10000
	s_addc_u32 s63, s65, 0
	s_add_i32 s68, s75, s2
	s_add_i32 s49, s68, 0x2000
	s_add_u32 s60, s66, 0x10080
	s_addc_u32 s61, s67, 0
	s_add_i32 s81, s74, s2
	s_add_i32 s80, s81, 0x2000
	v_lshl_add_u64 v[204:205], s[72:73], 0, v[136:137]
	ds_read_b128 v[172:175], v139
	ds_read_b128 v[176:179], v139 offset:1024
	ds_read_b128 v[180:183], v139 offset:2048
	ds_read_b128 v[184:187], v139 offset:3072
	ds_read_b128 v[188:191], v139 offset:4096
	ds_read_b128 v[192:195], v139 offset:5120
	ds_read_b128 v[196:199], v139 offset:6144
	ds_read_b128 v[214:217], v139 offset:7168
	s_setprio 1
	global_load_lds_dwordx4 v[204:205], off
	v_lshl_add_u64 v[204:205], s[72:73], 0, v[134:135]
	s_mov_b32 m0, s82
	s_nop 0
	global_load_lds_dwordx4 v[204:205], off
	s_waitcnt vmcnt(8)
	s_waitcnt lgkmcnt(0)
	s_barrier
	v_mfma_f32_16x16x32_bf16 v[128:131], v[140:143], v[172:175], v[128:131]
	v_mfma_f32_16x16x32_bf16 v[124:127], v[148:151], v[172:175], v[124:127]
	v_mfma_f32_16x16x32_bf16 v[120:123], v[140:143], v[180:183], v[120:123]
	v_mfma_f32_16x16x32_bf16 v[116:119], v[148:151], v[180:183], v[116:119]
	v_mfma_f32_16x16x32_bf16 v[104:107], v[140:143], v[188:191], v[104:107]
	v_mfma_f32_16x16x32_bf16 v[100:103], v[148:151], v[188:191], v[100:103]
	v_mfma_f32_16x16x32_bf16 v[86:89], v[140:143], v[196:199], v[86:89]
	v_mfma_f32_16x16x32_bf16 v[82:85], v[148:151], v[196:199], v[82:85]
	v_mfma_f32_16x16x32_bf16 v[128:131], v[144:147], v[176:179], v[128:131]
	v_mfma_f32_16x16x32_bf16 v[124:127], v[152:155], v[176:179], v[124:127]
	v_mfma_f32_16x16x32_bf16 v[120:123], v[144:147], v[184:187], v[120:123]
	v_mfma_f32_16x16x32_bf16 v[116:119], v[152:155], v[184:187], v[116:119]
	v_mfma_f32_16x16x32_bf16 v[104:107], v[144:147], v[192:195], v[104:107]
	v_mfma_f32_16x16x32_bf16 v[100:103], v[152:155], v[192:195], v[100:103]
	v_mfma_f32_16x16x32_bf16 v[86:89], v[144:147], v[214:217], v[86:89]
	v_mfma_f32_16x16x32_bf16 v[82:85], v[152:155], v[214:217], v[82:85]
	s_setprio 0
	s_setprio 1
	v_mfma_f32_16x16x32_bf16 v[112:115], v[156:159], v[172:175], v[112:115]
	v_mfma_f32_16x16x32_bf16 v[108:111], v[164:167], v[172:175], v[108:111]
	v_mfma_f32_16x16x32_bf16 v[94:97], v[156:159], v[180:183], v[94:97]
	v_mfma_f32_16x16x32_bf16 v[90:93], v[164:167], v[180:183], v[90:93]
	v_mfma_f32_16x16x32_bf16 v[78:81], v[156:159], v[188:191], v[78:81]
	v_mfma_f32_16x16x32_bf16 v[74:77], v[164:167], v[188:191], v[74:77]
	v_mfma_f32_16x16x32_bf16 v[70:73], v[156:159], v[196:199], v[70:73]
	v_mfma_f32_16x16x32_bf16 v[66:69], v[164:167], v[196:199], v[66:69]
	v_mfma_f32_16x16x32_bf16 v[112:115], v[160:163], v[176:179], v[112:115]
	v_mfma_f32_16x16x32_bf16 v[108:111], v[168:171], v[176:179], v[108:111]
	v_mfma_f32_16x16x32_bf16 v[94:97], v[160:163], v[184:187], v[94:97]
	v_mfma_f32_16x16x32_bf16 v[90:93], v[168:171], v[184:187], v[90:93]
	v_mfma_f32_16x16x32_bf16 v[78:81], v[160:163], v[192:195], v[78:81]
	v_mfma_f32_16x16x32_bf16 v[74:77], v[168:171], v[192:195], v[74:77]
	v_mfma_f32_16x16x32_bf16 v[70:73], v[160:163], v[214:217], v[70:73]
	v_mfma_f32_16x16x32_bf16 v[66:69], v[168:171], v[214:217], v[66:69]
	s_setprio 0
	s_barrier
	s_mov_b32 m0, s79
	v_lshl_add_u64 v[204:205], s[66:67], 0, v[98:99]
	ds_read_b128 v[172:175], v139 offset:16384
	ds_read_b128 v[176:179], v139 offset:17408
	ds_read_b128 v[180:183], v139 offset:18432
	ds_read_b128 v[184:187], v139 offset:19456
	ds_read_b128 v[188:191], v139 offset:20480
	ds_read_b128 v[192:195], v139 offset:21504
	ds_read_b128 v[196:199], v139 offset:22528
	ds_read_b128 v[214:217], v139 offset:23552
	s_setprio 1
	global_load_lds_dwordx4 v[204:205], off
	v_lshl_add_u64 v[206:207], s[66:67], 0, v[132:133]
	s_mov_b32 m0, s76
	v_lshl_add_u64 v[208:209], s[70:71], 0, v[98:99]
	global_load_lds_dwordx4 v[206:207], off
	s_mov_b32 m0, s78
	v_lshl_add_u64 v[210:211], s[64:65], 0, v[134:135]
	global_load_lds_dwordx4 v[208:209], off
	v_lshl_add_u64 v[208:209], s[70:71], 0, v[132:133]
	s_mov_b32 m0, s77
	s_nop 0
	global_load_lds_dwordx4 v[208:209], off
	v_lshl_add_u64 v[208:209], s[64:65], 0, v[136:137]
	s_mov_b32 m0, s4
	s_nop 0
	global_load_lds_dwordx4 v[208:209], off
	s_mov_b32 m0, s7
	s_nop 0
	global_load_lds_dwordx4 v[210:211], off
	s_waitcnt vmcnt(8)
	s_waitcnt lgkmcnt(0)
	s_barrier
	v_mfma_f32_16x16x32_bf16 v[62:65], v[140:143], v[172:175], v[62:65]
	v_mfma_f32_16x16x32_bf16 v[58:61], v[148:151], v[172:175], v[58:61]
	v_mfma_f32_16x16x32_bf16 v[54:57], v[140:143], v[180:183], v[54:57]
	v_mfma_f32_16x16x32_bf16 v[50:53], v[148:151], v[180:183], v[50:53]
	v_mfma_f32_16x16x32_bf16 v[38:41], v[140:143], v[188:191], v[38:41]
	v_mfma_f32_16x16x32_bf16 v[34:37], v[148:151], v[188:191], v[34:37]
	v_mfma_f32_16x16x32_bf16 v[22:25], v[140:143], v[196:199], v[22:25]
	v_mfma_f32_16x16x32_bf16 v[18:21], v[148:151], v[196:199], v[18:21]
	v_mfma_f32_16x16x32_bf16 v[62:65], v[144:147], v[176:179], v[62:65]
	v_mfma_f32_16x16x32_bf16 v[58:61], v[152:155], v[176:179], v[58:61]
	v_mfma_f32_16x16x32_bf16 v[54:57], v[144:147], v[184:187], v[54:57]
	v_mfma_f32_16x16x32_bf16 v[50:53], v[152:155], v[184:187], v[50:53]
	v_mfma_f32_16x16x32_bf16 v[38:41], v[144:147], v[192:195], v[38:41]
	v_mfma_f32_16x16x32_bf16 v[34:37], v[152:155], v[192:195], v[34:37]
	v_mfma_f32_16x16x32_bf16 v[22:25], v[144:147], v[214:217], v[22:25]
	v_mfma_f32_16x16x32_bf16 v[18:21], v[152:155], v[214:217], v[18:21]
	s_setprio 0
	s_setprio 1
	v_mfma_f32_16x16x32_bf16 v[46:49], v[156:159], v[172:175], v[46:49]
	v_mfma_f32_16x16x32_bf16 v[42:45], v[164:167], v[172:175], v[42:45]
	v_mfma_f32_16x16x32_bf16 v[30:33], v[156:159], v[180:183], v[30:33]
	v_mfma_f32_16x16x32_bf16 v[26:29], v[164:167], v[180:183], v[26:29]
	v_mfma_f32_16x16x32_bf16 v[14:17], v[156:159], v[188:191], v[14:17]
	v_mfma_f32_16x16x32_bf16 v[10:13], v[164:167], v[188:191], v[10:13]
	v_mfma_f32_16x16x32_bf16 v[6:9], v[156:159], v[196:199], v[6:9]
	v_mfma_f32_16x16x32_bf16 v[2:5], v[164:167], v[196:199], v[2:5]
	v_mfma_f32_16x16x32_bf16 v[46:49], v[160:163], v[176:179], v[46:49]
	v_mfma_f32_16x16x32_bf16 v[42:45], v[168:171], v[176:179], v[42:45]
	v_mfma_f32_16x16x32_bf16 v[30:33], v[160:163], v[184:187], v[30:33]
	v_mfma_f32_16x16x32_bf16 v[26:29], v[168:171], v[184:187], v[26:29]
	v_mfma_f32_16x16x32_bf16 v[14:17], v[160:163], v[192:195], v[14:17]
	v_mfma_f32_16x16x32_bf16 v[10:13], v[168:171], v[192:195], v[10:13]
	v_mfma_f32_16x16x32_bf16 v[6:9], v[160:163], v[214:217], v[6:9]
	v_mfma_f32_16x16x32_bf16 v[2:5], v[168:171], v[214:217], v[2:5]
	s_setprio 0
	s_barrier
	v_add_u32_e32 v152, s75, v138
	v_add_u32_e32 v168, s74, v138
	ds_read_b128 v[140:143], v152
	ds_read_b128 v[144:147], v152 offset:1024
	ds_read_b128 v[148:151], v152 offset:2048
	ds_read_b128 v[152:155], v152 offset:3072
	ds_read_b128 v[156:159], v168
	ds_read_b128 v[160:163], v168 offset:1024
	ds_read_b128 v[164:167], v168 offset:2048
	ds_read_b128 v[168:171], v168 offset:3072
	s_mov_b32 m0, s8
	v_lshl_add_u64 v[218:219], s[62:63], 0, v[136:137]
	ds_read_b128 v[172:175], v139 offset:32768
	ds_read_b128 v[176:179], v139 offset:33792
	ds_read_b128 v[180:183], v139 offset:34816
	ds_read_b128 v[184:187], v139 offset:35840
	ds_read_b128 v[188:191], v139 offset:36864
	ds_read_b128 v[192:195], v139 offset:37888
	ds_read_b128 v[196:199], v139 offset:38912
	ds_read_b128 v[214:217], v139 offset:39936
	s_setprio 1
	global_load_lds_dwordx4 v[218:219], off
	v_lshl_add_u64 v[218:219], s[62:63], 0, v[134:135]
	s_mov_b32 m0, s9
	s_nop 0
	global_load_lds_dwordx4 v[218:219], off
	s_waitcnt vmcnt(8)
	s_waitcnt lgkmcnt(0)
	s_barrier
	v_mfma_f32_16x16x32_bf16 v[128:131], v[140:143], v[172:175], v[128:131]
	v_mfma_f32_16x16x32_bf16 v[124:127], v[148:151], v[172:175], v[124:127]
	v_mfma_f32_16x16x32_bf16 v[120:123], v[140:143], v[180:183], v[120:123]
	v_mfma_f32_16x16x32_bf16 v[116:119], v[148:151], v[180:183], v[116:119]
	v_mfma_f32_16x16x32_bf16 v[104:107], v[140:143], v[188:191], v[104:107]
	v_mfma_f32_16x16x32_bf16 v[100:103], v[148:151], v[188:191], v[100:103]
	v_mfma_f32_16x16x32_bf16 v[86:89], v[140:143], v[196:199], v[86:89]
	v_mfma_f32_16x16x32_bf16 v[82:85], v[148:151], v[196:199], v[82:85]
	v_mfma_f32_16x16x32_bf16 v[128:131], v[144:147], v[176:179], v[128:131]
	v_mfma_f32_16x16x32_bf16 v[124:127], v[152:155], v[176:179], v[124:127]
	v_mfma_f32_16x16x32_bf16 v[120:123], v[144:147], v[184:187], v[120:123]
	v_mfma_f32_16x16x32_bf16 v[116:119], v[152:155], v[184:187], v[116:119]
	v_mfma_f32_16x16x32_bf16 v[104:107], v[144:147], v[192:195], v[104:107]
	v_mfma_f32_16x16x32_bf16 v[100:103], v[152:155], v[192:195], v[100:103]
	v_mfma_f32_16x16x32_bf16 v[86:89], v[144:147], v[214:217], v[86:89]
	v_mfma_f32_16x16x32_bf16 v[82:85], v[152:155], v[214:217], v[82:85]
	s_setprio 0
	s_setprio 1
	v_mfma_f32_16x16x32_bf16 v[112:115], v[156:159], v[172:175], v[112:115]
	v_mfma_f32_16x16x32_bf16 v[108:111], v[164:167], v[172:175], v[108:111]
	v_mfma_f32_16x16x32_bf16 v[94:97], v[156:159], v[180:183], v[94:97]
	v_mfma_f32_16x16x32_bf16 v[90:93], v[164:167], v[180:183], v[90:93]
	v_mfma_f32_16x16x32_bf16 v[78:81], v[156:159], v[188:191], v[78:81]
	v_mfma_f32_16x16x32_bf16 v[74:77], v[164:167], v[188:191], v[74:77]
	v_mfma_f32_16x16x32_bf16 v[70:73], v[156:159], v[196:199], v[70:73]
	v_mfma_f32_16x16x32_bf16 v[66:69], v[164:167], v[196:199], v[66:69]
	v_mfma_f32_16x16x32_bf16 v[112:115], v[160:163], v[176:179], v[112:115]
	v_mfma_f32_16x16x32_bf16 v[108:111], v[168:171], v[176:179], v[108:111]
	v_mfma_f32_16x16x32_bf16 v[94:97], v[160:163], v[184:187], v[94:97]
	v_mfma_f32_16x16x32_bf16 v[90:93], v[168:171], v[184:187], v[90:93]
	v_mfma_f32_16x16x32_bf16 v[78:81], v[160:163], v[192:195], v[78:81]
	v_mfma_f32_16x16x32_bf16 v[74:77], v[168:171], v[192:195], v[74:77]
	v_mfma_f32_16x16x32_bf16 v[70:73], v[160:163], v[214:217], v[70:73]
	v_mfma_f32_16x16x32_bf16 v[66:69], v[168:171], v[214:217], v[66:69]
	s_setprio 0
	s_barrier
	s_mov_b32 m0, s68
	v_lshl_add_u64 v[204:205], v[204:205], 0, s[28:29]
	ds_read_b128 v[172:175], v139 offset:49152
	ds_read_b128 v[176:179], v139 offset:50176
	ds_read_b128 v[180:183], v139 offset:51200
	ds_read_b128 v[184:187], v139 offset:52224
	ds_read_b128 v[188:191], v139 offset:53248
	ds_read_b128 v[192:195], v139 offset:54272
	ds_read_b128 v[196:199], v139 offset:55296
	ds_read_b128 v[214:217], v139 offset:56320
	s_setprio 1
	global_load_lds_dwordx4 v[204:205], off
	v_lshl_add_u64 v[204:205], v[206:207], 0, s[28:29]
	s_mov_b32 m0, s49
	s_nop 0
	global_load_lds_dwordx4 v[204:205], off
	v_lshl_add_u64 v[204:205], s[60:61], 0, v[98:99]
	s_mov_b32 m0, s81
	s_nop 0
	global_load_lds_dwordx4 v[204:205], off
	v_lshl_add_u64 v[204:205], s[60:61], 0, v[132:133]
	s_mov_b32 m0, s80
	s_nop 0
	global_load_lds_dwordx4 v[204:205], off
	v_lshl_add_u64 v[204:205], v[208:209], 0, s[28:29]
	s_mov_b32 m0, s10
	s_nop 0
	global_load_lds_dwordx4 v[204:205], off
	v_lshl_add_u64 v[204:205], v[210:211], 0, s[28:29]
	s_mov_b32 m0, s11
	s_nop 0
	global_load_lds_dwordx4 v[204:205], off
	s_waitcnt vmcnt(8)
	s_waitcnt lgkmcnt(0)
	s_barrier
	v_mfma_f32_16x16x32_bf16 v[62:65], v[140:143], v[172:175], v[62:65]
	v_mfma_f32_16x16x32_bf16 v[58:61], v[148:151], v[172:175], v[58:61]
	v_mfma_f32_16x16x32_bf16 v[54:57], v[140:143], v[180:183], v[54:57]
	v_mfma_f32_16x16x32_bf16 v[50:53], v[148:151], v[180:183], v[50:53]
	v_mfma_f32_16x16x32_bf16 v[38:41], v[140:143], v[188:191], v[38:41]
	v_mfma_f32_16x16x32_bf16 v[34:37], v[148:151], v[188:191], v[34:37]
	v_mfma_f32_16x16x32_bf16 v[22:25], v[140:143], v[196:199], v[22:25]
	v_mfma_f32_16x16x32_bf16 v[18:21], v[148:151], v[196:199], v[18:21]
	v_mfma_f32_16x16x32_bf16 v[62:65], v[144:147], v[176:179], v[62:65]
	v_mfma_f32_16x16x32_bf16 v[58:61], v[152:155], v[176:179], v[58:61]
	v_mfma_f32_16x16x32_bf16 v[54:57], v[144:147], v[184:187], v[54:57]
	v_mfma_f32_16x16x32_bf16 v[50:53], v[152:155], v[184:187], v[50:53]
	v_mfma_f32_16x16x32_bf16 v[38:41], v[144:147], v[192:195], v[38:41]
	v_mfma_f32_16x16x32_bf16 v[34:37], v[152:155], v[192:195], v[34:37]
	v_mfma_f32_16x16x32_bf16 v[22:25], v[144:147], v[214:217], v[22:25]
	v_mfma_f32_16x16x32_bf16 v[18:21], v[152:155], v[214:217], v[18:21]
	s_setprio 0
	s_setprio 1
	v_mfma_f32_16x16x32_bf16 v[46:49], v[156:159], v[172:175], v[46:49]
	v_mfma_f32_16x16x32_bf16 v[42:45], v[164:167], v[172:175], v[42:45]
	v_mfma_f32_16x16x32_bf16 v[30:33], v[156:159], v[180:183], v[30:33]
	v_mfma_f32_16x16x32_bf16 v[26:29], v[164:167], v[180:183], v[26:29]
	v_mfma_f32_16x16x32_bf16 v[14:17], v[156:159], v[188:191], v[14:17]
	v_mfma_f32_16x16x32_bf16 v[10:13], v[164:167], v[188:191], v[10:13]
	v_mfma_f32_16x16x32_bf16 v[6:9], v[156:159], v[196:199], v[6:9]
	v_mfma_f32_16x16x32_bf16 v[2:5], v[164:167], v[196:199], v[2:5]
	v_mfma_f32_16x16x32_bf16 v[46:49], v[160:163], v[176:179], v[46:49]
	v_mfma_f32_16x16x32_bf16 v[42:45], v[168:171], v[176:179], v[42:45]
	v_mfma_f32_16x16x32_bf16 v[30:33], v[160:163], v[184:187], v[30:33]
	v_mfma_f32_16x16x32_bf16 v[26:29], v[168:171], v[184:187], v[26:29]
	v_mfma_f32_16x16x32_bf16 v[14:17], v[160:163], v[192:195], v[14:17]
	v_mfma_f32_16x16x32_bf16 v[10:13], v[168:171], v[192:195], v[10:13]
	v_mfma_f32_16x16x32_bf16 v[6:9], v[160:163], v[214:217], v[6:9]
	v_mfma_f32_16x16x32_bf16 v[2:5], v[168:171], v[214:217], v[2:5]
	s_setprio 0
	s_barrier
	s_movk_i32 s49, 0x100
	s_andn2_b64 vcc, exec, s[58:59]
	s_mov_b64 s[60:61], -1
	s_mov_b64 s[58:59], 0
	s_cbranch_vccz .LBB0_333
	s_and_b64 vcc, exec, s[40:41]
	s_cbranch_vccz .LBB0_336
	s_barrier

.LBB0_438:
	s_add_u32 s42, s40, 0xfffc0080
	s_addc_u32 s43, s41, -1
	s_add_i32 s67, 0, 0x10000
	s_cmp_eq_u32 s66, 12
	s_cselect_b32 s45, s1, s43
	s_cselect_b32 s44, s49, s42
	s_cselect_b32 s43, s55, s65
	s_cselect_b32 s42, s63, s64
	s_add_i32 s72, 0, 0x14000
	v_add_u32_e32 v108, s67, v162
	v_add_u32_e32 v160, s72, v162
	ds_read_b128 v[90:93], v108
	ds_read_b128 v[94:97], v108 offset:1024
	ds_read_b128 v[100:103], v108 offset:2048
	ds_read_b128 v[108:111], v108 offset:3072
	ds_read_b128 v[166:169], v160
	ds_read_b128 v[170:173], v160 offset:1024
	ds_read_b128 v[174:177], v160 offset:2048
	ds_read_b128 v[178:181], v160 offset:3072
	v_lshl_add_u64 v[160:161], s[40:41], 0, v[156:157]
	s_add_i32 m0, s8, 0xc000
	ds_read_b128 v[182:185], v163
	ds_read_b128 v[186:189], v163 offset:1024
	ds_read_b128 v[190:193], v163 offset:2048
	ds_read_b128 v[194:197], v163 offset:3072
	ds_read_b128 v[214:217], v163 offset:4096
	ds_read_b128 v[218:221], v163 offset:5120
	ds_read_b128 v[222:225], v163 offset:6144
	ds_read_b128 v[226:229], v163 offset:7168
	s_setprio 1
	global_load_lds_dwordx4 v[160:161], off
	v_lshl_add_u64 v[160:161], s[40:41], 0, v[158:159]
	s_add_i32 m0, s8, 0xe000
	s_nop 0
	global_load_lds_dwordx4 v[160:161], off
	s_waitcnt vmcnt(8)
	s_waitcnt lgkmcnt(0)
	s_barrier
	v_mfma_f32_16x16x32_bf16 v[144:147], v[90:93], v[182:185], v[144:147]
	v_mfma_f32_16x16x32_bf16 v[140:143], v[100:103], v[182:185], v[140:143]
	v_mfma_f32_16x16x32_bf16 v[128:131], v[90:93], v[190:193], v[128:131]
	v_mfma_f32_16x16x32_bf16 v[124:127], v[100:103], v[190:193], v[124:127]
	v_mfma_f32_16x16x32_bf16 v[112:115], v[90:93], v[214:217], v[112:115]
	v_mfma_f32_16x16x32_bf16 v[104:107], v[100:103], v[214:217], v[104:107]
	v_mfma_f32_16x16x32_bf16 v[78:81], v[90:93], v[222:225], v[78:81]
	v_mfma_f32_16x16x32_bf16 v[74:77], v[100:103], v[222:225], v[74:77]
	v_mfma_f32_16x16x32_bf16 v[144:147], v[94:97], v[186:189], v[144:147]
	v_mfma_f32_16x16x32_bf16 v[140:143], v[108:111], v[186:189], v[140:143]
	v_mfma_f32_16x16x32_bf16 v[128:131], v[94:97], v[194:197], v[128:131]
	v_mfma_f32_16x16x32_bf16 v[124:127], v[108:111], v[194:197], v[124:127]
	v_mfma_f32_16x16x32_bf16 v[112:115], v[94:97], v[218:221], v[112:115]
	v_mfma_f32_16x16x32_bf16 v[104:107], v[108:111], v[218:221], v[104:107]
	v_mfma_f32_16x16x32_bf16 v[78:81], v[94:97], v[226:229], v[78:81]
	v_mfma_f32_16x16x32_bf16 v[74:77], v[108:111], v[226:229], v[74:77]
	s_setprio 0
	s_setprio 1
	v_mfma_f32_16x16x32_bf16 v[136:139], v[166:169], v[182:185], v[136:139]
	v_mfma_f32_16x16x32_bf16 v[132:135], v[174:177], v[182:185], v[132:135]
	v_mfma_f32_16x16x32_bf16 v[120:123], v[166:169], v[190:193], v[120:123]
	v_mfma_f32_16x16x32_bf16 v[116:119], v[174:177], v[190:193], v[116:119]
	v_mfma_f32_16x16x32_bf16 v[86:89], v[166:169], v[214:217], v[86:89]
	v_mfma_f32_16x16x32_bf16 v[82:85], v[174:177], v[214:217], v[82:85]
	v_mfma_f32_16x16x32_bf16 v[70:73], v[166:169], v[222:225], v[70:73]
	v_mfma_f32_16x16x32_bf16 v[66:69], v[174:177], v[222:225], v[66:69]
	v_mfma_f32_16x16x32_bf16 v[136:139], v[170:173], v[186:189], v[136:139]
	v_mfma_f32_16x16x32_bf16 v[132:135], v[178:181], v[186:189], v[132:135]
	v_mfma_f32_16x16x32_bf16 v[120:123], v[170:173], v[194:197], v[120:123]
	v_mfma_f32_16x16x32_bf16 v[116:119], v[178:181], v[194:197], v[116:119]
	v_mfma_f32_16x16x32_bf16 v[86:89], v[170:173], v[218:221], v[86:89]
	v_mfma_f32_16x16x32_bf16 v[82:85], v[178:181], v[218:221], v[82:85]
	v_mfma_f32_16x16x32_bf16 v[70:73], v[170:173], v[226:229], v[70:73]
	v_mfma_f32_16x16x32_bf16 v[66:69], v[178:181], v[226:229], v[66:69]
	s_setprio 0
	s_barrier
	s_add_i32 s67, s67, s7
	v_lshl_add_u64 v[160:161], s[42:43], 0, v[98:99]
	s_mov_b32 m0, s67
	ds_read_b128 v[182:185], v163 offset:16384
	ds_read_b128 v[186:189], v163 offset:17408
	ds_read_b128 v[190:193], v163 offset:18432
	ds_read_b128 v[194:197], v163 offset:19456
	ds_read_b128 v[214:217], v163 offset:20480
	ds_read_b128 v[218:221], v163 offset:21504
	ds_read_b128 v[222:225], v163 offset:22528
	ds_read_b128 v[226:229], v163 offset:23552
	s_setprio 1
	global_load_lds_dwordx4 v[160:161], off
	s_add_i32 m0, s67, 0x2000
	s_add_u32 s70, s42, 0x40000
	v_lshl_add_u64 v[198:199], s[42:43], 0, v[152:153]
	s_addc_u32 s71, s43, 0
	s_add_i32 s67, s72, s7
	global_load_lds_dwordx4 v[198:199], off
	v_lshl_add_u64 v[204:205], s[70:71], 0, v[98:99]
	s_mov_b32 m0, s67
	v_lshl_add_u64 v[206:207], s[44:45], 0, v[150:151]
	global_load_lds_dwordx4 v[204:205], off
	v_lshl_add_u64 v[204:205], s[70:71], 0, v[152:153]
	s_add_i32 m0, s67, 0x2000
	s_nop 0
	global_load_lds_dwordx4 v[204:205], off
	v_lshl_add_u64 v[204:205], s[44:45], 0, v[148:149]
	s_mov_b32 m0, s8
	s_nop 0
	global_load_lds_dwordx4 v[204:205], off
	s_mov_b32 m0, s9
	s_nop 0
	global_load_lds_dwordx4 v[206:207], off
	s_waitcnt vmcnt(8)
	s_waitcnt lgkmcnt(0)
	s_barrier
	v_mfma_f32_16x16x32_bf16 v[62:65], v[90:93], v[182:185], v[62:65]
	v_mfma_f32_16x16x32_bf16 v[58:61], v[100:103], v[182:185], v[58:61]
	v_mfma_f32_16x16x32_bf16 v[46:49], v[90:93], v[190:193], v[46:49]
	v_mfma_f32_16x16x32_bf16 v[42:45], v[100:103], v[190:193], v[42:45]
	v_mfma_f32_16x16x32_bf16 v[30:33], v[90:93], v[214:217], v[30:33]
	v_mfma_f32_16x16x32_bf16 v[26:29], v[100:103], v[214:217], v[26:29]
	v_mfma_f32_16x16x32_bf16 v[14:17], v[90:93], v[222:225], v[14:17]
	v_mfma_f32_16x16x32_bf16 v[10:13], v[100:103], v[222:225], v[10:13]
	v_mfma_f32_16x16x32_bf16 v[62:65], v[94:97], v[186:189], v[62:65]
	v_mfma_f32_16x16x32_bf16 v[58:61], v[108:111], v[186:189], v[58:61]
	v_mfma_f32_16x16x32_bf16 v[46:49], v[94:97], v[194:197], v[46:49]
	v_mfma_f32_16x16x32_bf16 v[42:45], v[108:111], v[194:197], v[42:45]
	v_mfma_f32_16x16x32_bf16 v[30:33], v[94:97], v[218:221], v[30:33]
	v_mfma_f32_16x16x32_bf16 v[26:29], v[108:111], v[218:221], v[26:29]
	v_mfma_f32_16x16x32_bf16 v[14:17], v[94:97], v[226:229], v[14:17]
	v_mfma_f32_16x16x32_bf16 v[10:13], v[108:111], v[226:229], v[10:13]
	s_setprio 0
	s_setprio 1
	v_mfma_f32_16x16x32_bf16 v[54:57], v[166:169], v[182:185], v[54:57]
	v_mfma_f32_16x16x32_bf16 v[50:53], v[174:177], v[182:185], v[50:53]
	v_mfma_f32_16x16x32_bf16 v[38:41], v[166:169], v[190:193], v[38:41]
	v_mfma_f32_16x16x32_bf16 v[34:37], v[174:177], v[190:193], v[34:37]
	v_mfma_f32_16x16x32_bf16 v[22:25], v[166:169], v[214:217], v[22:25]
	v_mfma_f32_16x16x32_bf16 v[18:21], v[174:177], v[214:217], v[18:21]
	v_mfma_f32_16x16x32_bf16 v[6:9], v[166:169], v[222:225], v[6:9]
	v_mfma_f32_16x16x32_bf16 v[2:5], v[174:177], v[222:225], v[2:5]
	v_mfma_f32_16x16x32_bf16 v[54:57], v[170:173], v[186:189], v[54:57]
	v_mfma_f32_16x16x32_bf16 v[50:53], v[178:181], v[186:189], v[50:53]
	v_mfma_f32_16x16x32_bf16 v[38:41], v[170:173], v[194:197], v[38:41]
	v_mfma_f32_16x16x32_bf16 v[34:37], v[178:181], v[194:197], v[34:37]
	v_mfma_f32_16x16x32_bf16 v[22:25], v[170:173], v[218:221], v[22:25]
	v_mfma_f32_16x16x32_bf16 v[18:21], v[178:181], v[218:221], v[18:21]
	v_mfma_f32_16x16x32_bf16 v[6:9], v[170:173], v[226:229], v[6:9]
	v_mfma_f32_16x16x32_bf16 v[2:5], v[178:181], v[226:229], v[2:5]
	s_setprio 0
	s_barrier
	s_add_i32 s67, 0, 0x18000
	s_add_i32 s70, 0, 0x1c000
	v_add_u32_e32 v108, s67, v162
	v_add_u32_e32 v165, s70, v162
	ds_read_b128 v[90:93], v108
	ds_read_b128 v[94:97], v108 offset:1024
	ds_read_b128 v[100:103], v108 offset:2048
	ds_read_b128 v[108:111], v108 offset:3072
	ds_read_b128 v[166:169], v165
	ds_read_b128 v[170:173], v165 offset:1024
	ds_read_b128 v[174:177], v165 offset:2048
	ds_read_b128 v[178:181], v165 offset:3072
	s_add_u32 s44, s44, 0x40000
	s_addc_u32 s45, s45, 0
	s_mov_b32 m0, s10
	v_lshl_add_u64 v[208:209], s[44:45], 0, v[148:149]
	ds_read_b128 v[182:185], v163 offset:32768
	ds_read_b128 v[186:189], v163 offset:33792
	ds_read_b128 v[190:193], v163 offset:34816
	ds_read_b128 v[194:197], v163 offset:35840
	ds_read_b128 v[214:217], v163 offset:36864
	ds_read_b128 v[218:221], v163 offset:37888
	ds_read_b128 v[222:225], v163 offset:38912
	ds_read_b128 v[226:229], v163 offset:39936
	s_setprio 1
	global_load_lds_dwordx4 v[208:209], off
	v_lshl_add_u64 v[208:209], s[44:45], 0, v[150:151]
	s_mov_b32 m0, s11
	s_nop 0
	global_load_lds_dwordx4 v[208:209], off
	s_waitcnt vmcnt(8)
	s_waitcnt lgkmcnt(0)
	s_barrier
	v_mfma_f32_16x16x32_bf16 v[144:147], v[90:93], v[182:185], v[144:147]
	v_mfma_f32_16x16x32_bf16 v[140:143], v[100:103], v[182:185], v[140:143]
	v_mfma_f32_16x16x32_bf16 v[128:131], v[90:93], v[190:193], v[128:131]
	v_mfma_f32_16x16x32_bf16 v[124:127], v[100:103], v[190:193], v[124:127]
	v_mfma_f32_16x16x32_bf16 v[112:115], v[90:93], v[214:217], v[112:115]
	v_mfma_f32_16x16x32_bf16 v[104:107], v[100:103], v[214:217], v[104:107]
	v_mfma_f32_16x16x32_bf16 v[78:81], v[90:93], v[222:225], v[78:81]
	v_mfma_f32_16x16x32_bf16 v[74:77], v[100:103], v[222:225], v[74:77]
	v_mfma_f32_16x16x32_bf16 v[144:147], v[94:97], v[186:189], v[144:147]
	v_mfma_f32_16x16x32_bf16 v[140:143], v[108:111], v[186:189], v[140:143]
	v_mfma_f32_16x16x32_bf16 v[128:131], v[94:97], v[194:197], v[128:131]
	v_mfma_f32_16x16x32_bf16 v[124:127], v[108:111], v[194:197], v[124:127]
	v_mfma_f32_16x16x32_bf16 v[112:115], v[94:97], v[218:221], v[112:115]
	v_mfma_f32_16x16x32_bf16 v[104:107], v[108:111], v[218:221], v[104:107]
	v_mfma_f32_16x16x32_bf16 v[78:81], v[94:97], v[226:229], v[78:81]
	v_mfma_f32_16x16x32_bf16 v[74:77], v[108:111], v[226:229], v[74:77]
	s_setprio 0
	s_setprio 1
	v_mfma_f32_16x16x32_bf16 v[136:139], v[166:169], v[182:185], v[136:139]
	v_mfma_f32_16x16x32_bf16 v[132:135], v[174:177], v[182:185], v[132:135]
	v_mfma_f32_16x16x32_bf16 v[120:123], v[166:169], v[190:193], v[120:123]
	v_mfma_f32_16x16x32_bf16 v[116:119], v[174:177], v[190:193], v[116:119]
	v_mfma_f32_16x16x32_bf16 v[86:89], v[166:169], v[214:217], v[86:89]
	v_mfma_f32_16x16x32_bf16 v[82:85], v[174:177], v[214:217], v[82:85]
	v_mfma_f32_16x16x32_bf16 v[70:73], v[166:169], v[222:225], v[70:73]
	v_mfma_f32_16x16x32_bf16 v[66:69], v[174:177], v[222:225], v[66:69]
	v_mfma_f32_16x16x32_bf16 v[136:139], v[170:173], v[186:189], v[136:139]
	v_mfma_f32_16x16x32_bf16 v[132:135], v[178:181], v[186:189], v[132:135]
	v_mfma_f32_16x16x32_bf16 v[120:123], v[170:173], v[194:197], v[120:123]
	v_mfma_f32_16x16x32_bf16 v[116:119], v[178:181], v[194:197], v[116:119]
	v_mfma_f32_16x16x32_bf16 v[86:89], v[170:173], v[218:221], v[86:89]
	v_mfma_f32_16x16x32_bf16 v[82:85], v[178:181], v[218:221], v[82:85]
	v_mfma_f32_16x16x32_bf16 v[70:73], v[170:173], v[226:229], v[70:73]
	v_mfma_f32_16x16x32_bf16 v[66:69], v[178:181], v[226:229], v[66:69]
	s_setprio 0
	s_barrier
	s_add_i32 s44, s67, s7
	v_lshl_add_u64 v[160:161], v[160:161], 0, s[28:29]
	s_mov_b32 m0, s44
	ds_read_b128 v[182:185], v163 offset:49152
	ds_read_b128 v[186:189], v163 offset:50176
	ds_read_b128 v[190:193], v163 offset:51200
	ds_read_b128 v[194:197], v163 offset:52224
	ds_read_b128 v[214:217], v163 offset:53248
	ds_read_b128 v[218:221], v163 offset:54272
	ds_read_b128 v[222:225], v163 offset:55296
	ds_read_b128 v[226:229], v163 offset:56320
	s_setprio 1
	global_load_lds_dwordx4 v[160:161], off
	s_add_i32 m0, s44, 0x2000
	s_add_u32 s42, s42, 0x40080
	v_lshl_add_u64 v[160:161], v[198:199], 0, s[28:29]
	s_addc_u32 s43, s43, 0
	s_add_i32 s44, s70, s7
	global_load_lds_dwordx4 v[160:161], off
	v_lshl_add_u64 v[160:161], s[42:43], 0, v[98:99]
	s_mov_b32 m0, s44
	s_nop 0
	global_load_lds_dwordx4 v[160:161], off
	v_lshl_add_u64 v[160:161], s[42:43], 0, v[152:153]
	s_add_i32 m0, s44, 0x2000
	s_nop 0
	global_load_lds_dwordx4 v[160:161], off
	v_lshl_add_u64 v[160:161], v[204:205], 0, s[28:29]
	s_mov_b32 m0, s16
	s_nop 0
	global_load_lds_dwordx4 v[160:161], off
	v_lshl_add_u64 v[160:161], v[206:207], 0, s[28:29]
	s_mov_b32 m0, s17
	s_nop 0
	global_load_lds_dwordx4 v[160:161], off
	s_waitcnt vmcnt(8)
	s_waitcnt lgkmcnt(0)
	s_barrier
	v_mfma_f32_16x16x32_bf16 v[62:65], v[90:93], v[182:185], v[62:65]
	v_mfma_f32_16x16x32_bf16 v[58:61], v[100:103], v[182:185], v[58:61]
	v_mfma_f32_16x16x32_bf16 v[46:49], v[90:93], v[190:193], v[46:49]
	v_mfma_f32_16x16x32_bf16 v[42:45], v[100:103], v[190:193], v[42:45]
	v_mfma_f32_16x16x32_bf16 v[30:33], v[90:93], v[214:217], v[30:33]
	v_mfma_f32_16x16x32_bf16 v[26:29], v[100:103], v[214:217], v[26:29]
	v_mfma_f32_16x16x32_bf16 v[14:17], v[90:93], v[222:225], v[14:17]
	v_mfma_f32_16x16x32_bf16 v[10:13], v[100:103], v[222:225], v[10:13]
	v_mfma_f32_16x16x32_bf16 v[62:65], v[94:97], v[186:189], v[62:65]
	v_mfma_f32_16x16x32_bf16 v[58:61], v[108:111], v[186:189], v[58:61]
	v_mfma_f32_16x16x32_bf16 v[46:49], v[94:97], v[194:197], v[46:49]
	v_mfma_f32_16x16x32_bf16 v[42:45], v[108:111], v[194:197], v[42:45]
	v_mfma_f32_16x16x32_bf16 v[30:33], v[94:97], v[218:221], v[30:33]
	v_mfma_f32_16x16x32_bf16 v[26:29], v[108:111], v[218:221], v[26:29]
	v_mfma_f32_16x16x32_bf16 v[14:17], v[94:97], v[226:229], v[14:17]
	v_mfma_f32_16x16x32_bf16 v[10:13], v[108:111], v[226:229], v[10:13]
	s_setprio 0
	s_setprio 1
	v_mfma_f32_16x16x32_bf16 v[54:57], v[166:169], v[182:185], v[54:57]
	v_mfma_f32_16x16x32_bf16 v[50:53], v[174:177], v[182:185], v[50:53]
	v_mfma_f32_16x16x32_bf16 v[38:41], v[166:169], v[190:193], v[38:41]
	v_mfma_f32_16x16x32_bf16 v[34:37], v[174:177], v[190:193], v[34:37]
	v_mfma_f32_16x16x32_bf16 v[22:25], v[166:169], v[214:217], v[22:25]
	v_mfma_f32_16x16x32_bf16 v[18:21], v[174:177], v[214:217], v[18:21]
	v_mfma_f32_16x16x32_bf16 v[6:9], v[166:169], v[222:225], v[6:9]
	v_mfma_f32_16x16x32_bf16 v[2:5], v[174:177], v[222:225], v[2:5]
	v_mfma_f32_16x16x32_bf16 v[54:57], v[170:173], v[186:189], v[54:57]
	v_mfma_f32_16x16x32_bf16 v[50:53], v[178:181], v[186:189], v[50:53]
	v_mfma_f32_16x16x32_bf16 v[38:41], v[170:173], v[194:197], v[38:41]
	v_mfma_f32_16x16x32_bf16 v[34:37], v[178:181], v[194:197], v[34:37]
	v_mfma_f32_16x16x32_bf16 v[22:25], v[170:173], v[218:221], v[22:25]
	v_mfma_f32_16x16x32_bf16 v[18:21], v[178:181], v[218:221], v[18:21]
	v_mfma_f32_16x16x32_bf16 v[6:9], v[170:173], v[226:229], v[6:9]
	v_mfma_f32_16x16x32_bf16 v[2:5], v[178:181], v[226:229], v[2:5]
	s_setprio 0
	s_barrier
	s_add_i32 s66, s66, 2
	s_add_u32 s40, s40, 0x100
	s_addc_u32 s41, s41, 0
	s_add_u32 s64, s64, 0x100
	s_addc_u32 s65, s65, 0
	s_cmp_gt_u32 s66, 13
	s_cbranch_scc0 .LBB0_438
	s_and_b64 vcc, exec, s[22:23]
	s_cbranch_vccz .LBB0_441
	s_barrier

.LBB0_647:
	s_add_i32 s68, s42, 2
	s_add_u32 s43, s40, 0xfff80080
	s_addc_u32 s54, s41, -1
	s_add_i32 s70, 0, 0x10000
	s_cmp_eq_u32 s65, s42
	s_cselect_b32 s55, s49, s54
	s_cselect_b32 s54, s63, s43
	v_add_u32_e32 v146, s70, v149
	s_cselect_b32 s43, s51, s67
	s_cselect_b32 s42, s50, s66
	s_add_i32 s72, 0, 0x14000
	ds_read_b128 v[152:155], v146
	ds_read_b128 v[156:159], v146 offset:1024
	ds_read_b128 v[160:163], v146 offset:2048
	ds_read_b128 v[164:167], v146 offset:3072
	v_add_u32_e32 v146, s72, v149
	ds_read_b128 v[168:171], v146
	ds_read_b128 v[172:175], v146 offset:1024
	ds_read_b128 v[176:179], v146 offset:2048
	ds_read_b128 v[180:183], v146 offset:3072
	v_lshl_add_u64 v[146:147], s[40:41], 0, v[142:143]
	s_add_i32 m0, s11, 0xc000
	ds_read_b128 v[184:187], v150
	ds_read_b128 v[188:191], v150 offset:1024
	ds_read_b128 v[192:195], v150 offset:2048
	ds_read_b128 v[196:199], v150 offset:3072
	ds_read_b128 v[214:217], v150 offset:4096
	ds_read_b128 v[218:221], v150 offset:5120
	ds_read_b128 v[222:225], v150 offset:6144
	ds_read_b128 v[226:229], v150 offset:7168
	s_setprio 1
	global_load_lds_dwordx4 v[146:147], off
	v_lshl_add_u64 v[146:147], s[40:41], 0, v[144:145]
	s_add_i32 m0, s11, 0xe000
	s_nop 0
	global_load_lds_dwordx4 v[146:147], off
	s_waitcnt vmcnt(8)
	s_waitcnt lgkmcnt(0)
	s_barrier
	v_mfma_f32_16x16x32_bf16 v[128:131], v[152:155], v[184:187], v[128:131]
	v_mfma_f32_16x16x32_bf16 v[124:127], v[160:163], v[184:187], v[124:127]
	v_mfma_f32_16x16x32_bf16 v[112:115], v[152:155], v[192:195], v[112:115]
	v_mfma_f32_16x16x32_bf16 v[108:111], v[160:163], v[192:195], v[108:111]
	v_mfma_f32_16x16x32_bf16 v[94:97], v[152:155], v[214:217], v[94:97]
	v_mfma_f32_16x16x32_bf16 v[90:93], v[160:163], v[214:217], v[90:93]
	v_mfma_f32_16x16x32_bf16 v[78:81], v[152:155], v[222:225], v[78:81]
	v_mfma_f32_16x16x32_bf16 v[74:77], v[160:163], v[222:225], v[74:77]
	v_mfma_f32_16x16x32_bf16 v[128:131], v[156:159], v[188:191], v[128:131]
	v_mfma_f32_16x16x32_bf16 v[124:127], v[164:167], v[188:191], v[124:127]
	v_mfma_f32_16x16x32_bf16 v[112:115], v[156:159], v[196:199], v[112:115]
	v_mfma_f32_16x16x32_bf16 v[108:111], v[164:167], v[196:199], v[108:111]
	v_mfma_f32_16x16x32_bf16 v[94:97], v[156:159], v[218:221], v[94:97]
	v_mfma_f32_16x16x32_bf16 v[90:93], v[164:167], v[218:221], v[90:93]
	v_mfma_f32_16x16x32_bf16 v[78:81], v[156:159], v[226:229], v[78:81]
	v_mfma_f32_16x16x32_bf16 v[74:77], v[164:167], v[226:229], v[74:77]
	s_setprio 0
	s_setprio 1
	v_mfma_f32_16x16x32_bf16 v[120:123], v[168:171], v[184:187], v[120:123]
	v_mfma_f32_16x16x32_bf16 v[116:119], v[176:179], v[184:187], v[116:119]
	v_mfma_f32_16x16x32_bf16 v[104:107], v[168:171], v[192:195], v[104:107]
	v_mfma_f32_16x16x32_bf16 v[100:103], v[176:179], v[192:195], v[100:103]
	v_mfma_f32_16x16x32_bf16 v[86:89], v[168:171], v[214:217], v[86:89]
	v_mfma_f32_16x16x32_bf16 v[82:85], v[176:179], v[214:217], v[82:85]
	v_mfma_f32_16x16x32_bf16 v[70:73], v[168:171], v[222:225], v[70:73]
	v_mfma_f32_16x16x32_bf16 v[66:69], v[176:179], v[222:225], v[66:69]
	v_mfma_f32_16x16x32_bf16 v[120:123], v[172:175], v[188:191], v[120:123]
	v_mfma_f32_16x16x32_bf16 v[116:119], v[180:183], v[188:191], v[116:119]
	v_mfma_f32_16x16x32_bf16 v[104:107], v[172:175], v[196:199], v[104:107]
	v_mfma_f32_16x16x32_bf16 v[100:103], v[180:183], v[196:199], v[100:103]
	v_mfma_f32_16x16x32_bf16 v[86:89], v[172:175], v[218:221], v[86:89]
	v_mfma_f32_16x16x32_bf16 v[82:85], v[180:183], v[218:221], v[82:85]
	v_mfma_f32_16x16x32_bf16 v[70:73], v[172:175], v[226:229], v[70:73]
	v_mfma_f32_16x16x32_bf16 v[66:69], v[180:183], v[226:229], v[66:69]
	s_setprio 0
	s_barrier
	s_add_i32 s70, s70, s10
	v_lshl_add_u64 v[146:147], s[42:43], 0, v[98:99]
	s_mov_b32 m0, s70
	ds_read_b128 v[184:187], v150 offset:16384
	ds_read_b128 v[188:191], v150 offset:17408
	ds_read_b128 v[192:195], v150 offset:18432
	ds_read_b128 v[196:199], v150 offset:19456
	ds_read_b128 v[214:217], v150 offset:20480
	ds_read_b128 v[218:221], v150 offset:21504
	ds_read_b128 v[222:225], v150 offset:22528
	ds_read_b128 v[226:229], v150 offset:23552
	s_setprio 1
	global_load_lds_dwordx4 v[146:147], off
	s_add_i32 m0, s70, 0x2000
	s_add_u32 s70, s42, 0x18000
	v_lshl_add_u64 v[204:205], s[42:43], 0, v[136:137]
	s_addc_u32 s71, s43, 0
	s_add_i32 s72, s72, s10
	global_load_lds_dwordx4 v[204:205], off
	v_lshl_add_u64 v[206:207], s[70:71], 0, v[98:99]
	s_mov_b32 m0, s72
	v_lshl_add_u64 v[208:209], s[54:55], 0, v[134:135]
	global_load_lds_dwordx4 v[206:207], off
	v_lshl_add_u64 v[206:207], s[70:71], 0, v[136:137]
	s_add_i32 m0, s72, 0x2000
	s_nop 0
	global_load_lds_dwordx4 v[206:207], off
	v_lshl_add_u64 v[206:207], s[54:55], 0, v[132:133]
	s_mov_b32 m0, s11
	s_nop 0
	global_load_lds_dwordx4 v[206:207], off
	s_mov_b32 m0, s12
	s_nop 0
	global_load_lds_dwordx4 v[208:209], off
	s_waitcnt vmcnt(8)
	s_waitcnt lgkmcnt(0)
	s_barrier
	v_mfma_f32_16x16x32_bf16 v[62:65], v[152:155], v[184:187], v[62:65]
	v_mfma_f32_16x16x32_bf16 v[58:61], v[160:163], v[184:187], v[58:61]
	v_mfma_f32_16x16x32_bf16 v[46:49], v[152:155], v[192:195], v[46:49]
	v_mfma_f32_16x16x32_bf16 v[42:45], v[160:163], v[192:195], v[42:45]
	v_mfma_f32_16x16x32_bf16 v[30:33], v[152:155], v[214:217], v[30:33]
	v_mfma_f32_16x16x32_bf16 v[26:29], v[160:163], v[214:217], v[26:29]
	v_mfma_f32_16x16x32_bf16 v[14:17], v[152:155], v[222:225], v[14:17]
	v_mfma_f32_16x16x32_bf16 v[10:13], v[160:163], v[222:225], v[10:13]
	v_mfma_f32_16x16x32_bf16 v[62:65], v[156:159], v[188:191], v[62:65]
	v_mfma_f32_16x16x32_bf16 v[58:61], v[164:167], v[188:191], v[58:61]
	v_mfma_f32_16x16x32_bf16 v[46:49], v[156:159], v[196:199], v[46:49]
	v_mfma_f32_16x16x32_bf16 v[42:45], v[164:167], v[196:199], v[42:45]
	v_mfma_f32_16x16x32_bf16 v[30:33], v[156:159], v[218:221], v[30:33]
	v_mfma_f32_16x16x32_bf16 v[26:29], v[164:167], v[218:221], v[26:29]
	v_mfma_f32_16x16x32_bf16 v[14:17], v[156:159], v[226:229], v[14:17]
	v_mfma_f32_16x16x32_bf16 v[10:13], v[164:167], v[226:229], v[10:13]
	s_setprio 0
	s_setprio 1
	v_mfma_f32_16x16x32_bf16 v[54:57], v[168:171], v[184:187], v[54:57]
	v_mfma_f32_16x16x32_bf16 v[50:53], v[176:179], v[184:187], v[50:53]
	v_mfma_f32_16x16x32_bf16 v[38:41], v[168:171], v[192:195], v[38:41]
	v_mfma_f32_16x16x32_bf16 v[34:37], v[176:179], v[192:195], v[34:37]
	v_mfma_f32_16x16x32_bf16 v[22:25], v[168:171], v[214:217], v[22:25]
	v_mfma_f32_16x16x32_bf16 v[18:21], v[176:179], v[214:217], v[18:21]
	v_mfma_f32_16x16x32_bf16 v[6:9], v[168:171], v[222:225], v[6:9]
	v_mfma_f32_16x16x32_bf16 v[2:5], v[176:179], v[222:225], v[2:5]
	v_mfma_f32_16x16x32_bf16 v[54:57], v[172:175], v[188:191], v[54:57]
	v_mfma_f32_16x16x32_bf16 v[50:53], v[180:183], v[188:191], v[50:53]
	v_mfma_f32_16x16x32_bf16 v[38:41], v[172:175], v[196:199], v[38:41]
	v_mfma_f32_16x16x32_bf16 v[34:37], v[180:183], v[196:199], v[34:37]
	v_mfma_f32_16x16x32_bf16 v[22:25], v[172:175], v[218:221], v[22:25]
	v_mfma_f32_16x16x32_bf16 v[18:21], v[180:183], v[218:221], v[18:21]
	v_mfma_f32_16x16x32_bf16 v[6:9], v[172:175], v[226:229], v[6:9]
	v_mfma_f32_16x16x32_bf16 v[2:5], v[180:183], v[226:229], v[2:5]
	s_setprio 0
	s_barrier
	s_add_i32 s70, 0, 0x18000
	v_add_u32_e32 v151, s70, v149
	s_add_i32 s71, 0, 0x1c000
	ds_read_b128 v[152:155], v151
	ds_read_b128 v[156:159], v151 offset:1024
	ds_read_b128 v[160:163], v151 offset:2048
	ds_read_b128 v[164:167], v151 offset:3072
	v_add_u32_e32 v151, s71, v149
	ds_read_b128 v[168:171], v151
	ds_read_b128 v[172:175], v151 offset:1024
	ds_read_b128 v[176:179], v151 offset:2048
	ds_read_b128 v[180:183], v151 offset:3072
	s_add_u32 s54, s54, 0x80000
	s_addc_u32 s55, s55, 0
	s_mov_b32 m0, s13
	v_lshl_add_u64 v[210:211], s[54:55], 0, v[132:133]
	ds_read_b128 v[184:187], v150 offset:32768
	ds_read_b128 v[188:191], v150 offset:33792
	ds_read_b128 v[192:195], v150 offset:34816
	ds_read_b128 v[196:199], v150 offset:35840
	ds_read_b128 v[214:217], v150 offset:36864
	ds_read_b128 v[218:221], v150 offset:37888
	ds_read_b128 v[222:225], v150 offset:38912
	ds_read_b128 v[226:229], v150 offset:39936
	s_setprio 1
	global_load_lds_dwordx4 v[210:211], off
	v_lshl_add_u64 v[210:211], s[54:55], 0, v[134:135]
	s_mov_b32 m0, s14
	s_nop 0
	global_load_lds_dwordx4 v[210:211], off
	s_waitcnt vmcnt(8)
	s_waitcnt lgkmcnt(0)
	s_barrier
	v_mfma_f32_16x16x32_bf16 v[128:131], v[152:155], v[184:187], v[128:131]
	v_mfma_f32_16x16x32_bf16 v[124:127], v[160:163], v[184:187], v[124:127]
	v_mfma_f32_16x16x32_bf16 v[112:115], v[152:155], v[192:195], v[112:115]
	v_mfma_f32_16x16x32_bf16 v[108:111], v[160:163], v[192:195], v[108:111]
	v_mfma_f32_16x16x32_bf16 v[94:97], v[152:155], v[214:217], v[94:97]
	v_mfma_f32_16x16x32_bf16 v[90:93], v[160:163], v[214:217], v[90:93]
	v_mfma_f32_16x16x32_bf16 v[78:81], v[152:155], v[222:225], v[78:81]
	v_mfma_f32_16x16x32_bf16 v[74:77], v[160:163], v[222:225], v[74:77]
	v_mfma_f32_16x16x32_bf16 v[128:131], v[156:159], v[188:191], v[128:131]
	v_mfma_f32_16x16x32_bf16 v[124:127], v[164:167], v[188:191], v[124:127]
	v_mfma_f32_16x16x32_bf16 v[112:115], v[156:159], v[196:199], v[112:115]
	v_mfma_f32_16x16x32_bf16 v[108:111], v[164:167], v[196:199], v[108:111]
	v_mfma_f32_16x16x32_bf16 v[94:97], v[156:159], v[218:221], v[94:97]
	v_mfma_f32_16x16x32_bf16 v[90:93], v[164:167], v[218:221], v[90:93]
	v_mfma_f32_16x16x32_bf16 v[78:81], v[156:159], v[226:229], v[78:81]
	v_mfma_f32_16x16x32_bf16 v[74:77], v[164:167], v[226:229], v[74:77]
	s_setprio 0
	s_setprio 1
	v_mfma_f32_16x16x32_bf16 v[120:123], v[168:171], v[184:187], v[120:123]
	v_mfma_f32_16x16x32_bf16 v[116:119], v[176:179], v[184:187], v[116:119]
	v_mfma_f32_16x16x32_bf16 v[104:107], v[168:171], v[192:195], v[104:107]
	v_mfma_f32_16x16x32_bf16 v[100:103], v[176:179], v[192:195], v[100:103]
	v_mfma_f32_16x16x32_bf16 v[86:89], v[168:171], v[214:217], v[86:89]
	v_mfma_f32_16x16x32_bf16 v[82:85], v[176:179], v[214:217], v[82:85]
	v_mfma_f32_16x16x32_bf16 v[70:73], v[168:171], v[222:225], v[70:73]
	v_mfma_f32_16x16x32_bf16 v[66:69], v[176:179], v[222:225], v[66:69]
	v_mfma_f32_16x16x32_bf16 v[120:123], v[172:175], v[188:191], v[120:123]
	v_mfma_f32_16x16x32_bf16 v[116:119], v[180:183], v[188:191], v[116:119]
	v_mfma_f32_16x16x32_bf16 v[104:107], v[172:175], v[196:199], v[104:107]
	v_mfma_f32_16x16x32_bf16 v[100:103], v[180:183], v[196:199], v[100:103]
	v_mfma_f32_16x16x32_bf16 v[86:89], v[172:175], v[218:221], v[86:89]
	v_mfma_f32_16x16x32_bf16 v[82:85], v[180:183], v[218:221], v[82:85]
	v_mfma_f32_16x16x32_bf16 v[70:73], v[172:175], v[226:229], v[70:73]
	v_mfma_f32_16x16x32_bf16 v[66:69], v[180:183], v[226:229], v[66:69]
	s_setprio 0
	s_barrier
	s_add_i32 s54, s70, s10
	v_lshl_add_u64 v[146:147], v[146:147], 0, s[28:29]
	s_mov_b32 m0, s54
	ds_read_b128 v[184:187], v150 offset:49152
	ds_read_b128 v[188:191], v150 offset:50176
	ds_read_b128 v[192:195], v150 offset:51200
	ds_read_b128 v[196:199], v150 offset:52224
	ds_read_b128 v[214:217], v150 offset:53248
	ds_read_b128 v[218:221], v150 offset:54272
	ds_read_b128 v[222:225], v150 offset:55296
	ds_read_b128 v[226:229], v150 offset:56320
	s_setprio 1
	global_load_lds_dwordx4 v[146:147], off
	s_add_i32 m0, s54, 0x2000
	s_add_u32 s42, s42, 0x18080
	v_lshl_add_u64 v[146:147], v[204:205], 0, s[28:29]
	s_addc_u32 s43, s43, 0
	s_add_i32 s54, s71, s10
	global_load_lds_dwordx4 v[146:147], off
	v_lshl_add_u64 v[146:147], s[42:43], 0, v[98:99]
	s_mov_b32 m0, s54
	s_nop 0
	global_load_lds_dwordx4 v[146:147], off
	v_lshl_add_u64 v[146:147], s[42:43], 0, v[136:137]
	s_add_i32 m0, s54, 0x2000
	s_nop 0
	global_load_lds_dwordx4 v[146:147], off
	v_lshl_add_u64 v[146:147], v[206:207], 0, s[28:29]
	s_mov_b32 m0, s17
	s_nop 0
	global_load_lds_dwordx4 v[146:147], off
	v_lshl_add_u64 v[146:147], v[208:209], 0, s[28:29]
	s_mov_b32 m0, s18
	s_nop 0
	global_load_lds_dwordx4 v[146:147], off
	s_waitcnt vmcnt(8)
	s_waitcnt lgkmcnt(0)
	s_barrier
	v_mfma_f32_16x16x32_bf16 v[62:65], v[152:155], v[184:187], v[62:65]
	v_mfma_f32_16x16x32_bf16 v[58:61], v[160:163], v[184:187], v[58:61]
	v_mfma_f32_16x16x32_bf16 v[46:49], v[152:155], v[192:195], v[46:49]
	v_mfma_f32_16x16x32_bf16 v[42:45], v[160:163], v[192:195], v[42:45]
	v_mfma_f32_16x16x32_bf16 v[30:33], v[152:155], v[214:217], v[30:33]
	v_mfma_f32_16x16x32_bf16 v[26:29], v[160:163], v[214:217], v[26:29]
	v_mfma_f32_16x16x32_bf16 v[14:17], v[152:155], v[222:225], v[14:17]
	v_mfma_f32_16x16x32_bf16 v[10:13], v[160:163], v[222:225], v[10:13]
	v_mfma_f32_16x16x32_bf16 v[62:65], v[156:159], v[188:191], v[62:65]
	v_mfma_f32_16x16x32_bf16 v[58:61], v[164:167], v[188:191], v[58:61]
	v_mfma_f32_16x16x32_bf16 v[46:49], v[156:159], v[196:199], v[46:49]
	v_mfma_f32_16x16x32_bf16 v[42:45], v[164:167], v[196:199], v[42:45]
	v_mfma_f32_16x16x32_bf16 v[30:33], v[156:159], v[218:221], v[30:33]
	v_mfma_f32_16x16x32_bf16 v[26:29], v[164:167], v[218:221], v[26:29]
	v_mfma_f32_16x16x32_bf16 v[14:17], v[156:159], v[226:229], v[14:17]
	v_mfma_f32_16x16x32_bf16 v[10:13], v[164:167], v[226:229], v[10:13]
	s_setprio 0
	s_setprio 1
	v_mfma_f32_16x16x32_bf16 v[54:57], v[168:171], v[184:187], v[54:57]
	v_mfma_f32_16x16x32_bf16 v[50:53], v[176:179], v[184:187], v[50:53]
	v_mfma_f32_16x16x32_bf16 v[38:41], v[168:171], v[192:195], v[38:41]
	v_mfma_f32_16x16x32_bf16 v[34:37], v[176:179], v[192:195], v[34:37]
	v_mfma_f32_16x16x32_bf16 v[22:25], v[168:171], v[214:217], v[22:25]
	v_mfma_f32_16x16x32_bf16 v[18:21], v[176:179], v[214:217], v[18:21]
	v_mfma_f32_16x16x32_bf16 v[6:9], v[168:171], v[222:225], v[6:9]
	v_mfma_f32_16x16x32_bf16 v[2:5], v[176:179], v[222:225], v[2:5]
	v_mfma_f32_16x16x32_bf16 v[54:57], v[172:175], v[188:191], v[54:57]
	v_mfma_f32_16x16x32_bf16 v[50:53], v[180:183], v[188:191], v[50:53]
	v_mfma_f32_16x16x32_bf16 v[38:41], v[172:175], v[196:199], v[38:41]
	v_mfma_f32_16x16x32_bf16 v[34:37], v[180:183], v[196:199], v[34:37]
	v_mfma_f32_16x16x32_bf16 v[22:25], v[172:175], v[218:221], v[22:25]
	v_mfma_f32_16x16x32_bf16 v[18:21], v[180:183], v[218:221], v[18:21]
	v_mfma_f32_16x16x32_bf16 v[6:9], v[172:175], v[226:229], v[6:9]
	v_mfma_f32_16x16x32_bf16 v[2:5], v[180:183], v[226:229], v[2:5]
	s_setprio 0
	s_barrier
	s_add_u32 s40, s40, 0x100
	s_addc_u32 s41, s41, 0
	s_add_u32 s66, s66, 0x100
	s_addc_u32 s67, s67, 0
	s_cmp_ge_i32 s68, s62
	s_mov_b32 s42, s68
	s_cbranch_scc0 .LBB0_647
	s_and_b64 vcc, exec, s[44:45]
	s_cbranch_vccz .LBB0_650
	s_barrier

.LBB0_893:
	s_add_u32 s50, s48, 0xfffe0080
	s_addc_u32 s51, s49, -1
	s_add_i32 s57, 0, 0x10000
	s_cmp_eq_u32 s56, 4
	s_cselect_b32 s53, s19, s51
	s_cselect_b32 s52, s33, s50
	v_add_u32_e32 v98, s57, v144
	s_cselect_b32 s51, s37, s55
	s_cselect_b32 s50, s39, s54
	s_add_i32 s60, 0, 0x14000
	ds_read_b128 v[146:149], v98
	ds_read_b128 v[150:153], v98 offset:1024
	ds_read_b128 v[154:157], v98 offset:2048
	ds_read_b128 v[158:161], v98 offset:3072
	v_add_u32_e32 v98, s60, v144
	ds_read_b128 v[162:165], v98
	ds_read_b128 v[166:169], v98 offset:1024
	ds_read_b128 v[170:173], v98 offset:2048
	ds_read_b128 v[174:177], v98 offset:3072
	v_lshl_add_u64 v[198:199], s[48:49], 0, v[140:141]
	s_add_i32 m0, s4, 0xc000
	ds_read_b128 v[178:181], v145
	ds_read_b128 v[182:185], v145 offset:1024
	ds_read_b128 v[186:189], v145 offset:2048
	ds_read_b128 v[190:193], v145 offset:3072
	ds_read_b128 v[194:197], v145 offset:4096
	ds_read_b128 v[204:207], v145 offset:5120
	ds_read_b128 v[208:211], v145 offset:6144
	ds_read_b128 v[214:217], v145 offset:7168
	s_setprio 1
	global_load_lds_dwordx4 v[198:199], off
	v_lshl_add_u64 v[198:199], s[48:49], 0, v[142:143]
	s_add_i32 m0, s4, 0xe000
	s_nop 0
	global_load_lds_dwordx4 v[198:199], off
	s_waitcnt vmcnt(8)
	s_waitcnt lgkmcnt(0)
	s_barrier
	v_mfma_f32_16x16x32_bf16 v[128:131], v[146:149], v[178:181], v[128:131]
	v_mfma_f32_16x16x32_bf16 v[124:127], v[154:157], v[178:181], v[124:127]
	v_mfma_f32_16x16x32_bf16 v[112:115], v[146:149], v[186:189], v[112:115]
	v_mfma_f32_16x16x32_bf16 v[108:111], v[154:157], v[186:189], v[108:111]
	v_mfma_f32_16x16x32_bf16 v[94:97], v[146:149], v[194:197], v[94:97]
	v_mfma_f32_16x16x32_bf16 v[90:93], v[154:157], v[194:197], v[90:93]
	v_mfma_f32_16x16x32_bf16 v[78:81], v[146:149], v[208:211], v[78:81]
	v_mfma_f32_16x16x32_bf16 v[74:77], v[154:157], v[208:211], v[74:77]
	v_mfma_f32_16x16x32_bf16 v[128:131], v[150:153], v[182:185], v[128:131]
	v_mfma_f32_16x16x32_bf16 v[124:127], v[158:161], v[182:185], v[124:127]
	v_mfma_f32_16x16x32_bf16 v[112:115], v[150:153], v[190:193], v[112:115]
	v_mfma_f32_16x16x32_bf16 v[108:111], v[158:161], v[190:193], v[108:111]
	v_mfma_f32_16x16x32_bf16 v[94:97], v[150:153], v[204:207], v[94:97]
	v_mfma_f32_16x16x32_bf16 v[90:93], v[158:161], v[204:207], v[90:93]
	v_mfma_f32_16x16x32_bf16 v[78:81], v[150:153], v[214:217], v[78:81]
	v_mfma_f32_16x16x32_bf16 v[74:77], v[158:161], v[214:217], v[74:77]
	s_setprio 0
	s_setprio 1
	v_mfma_f32_16x16x32_bf16 v[120:123], v[162:165], v[178:181], v[120:123]
	v_mfma_f32_16x16x32_bf16 v[116:119], v[170:173], v[178:181], v[116:119]
	v_mfma_f32_16x16x32_bf16 v[104:107], v[162:165], v[186:189], v[104:107]
	v_mfma_f32_16x16x32_bf16 v[100:103], v[170:173], v[186:189], v[100:103]
	v_mfma_f32_16x16x32_bf16 v[86:89], v[162:165], v[194:197], v[86:89]
	v_mfma_f32_16x16x32_bf16 v[82:85], v[170:173], v[194:197], v[82:85]
	v_mfma_f32_16x16x32_bf16 v[70:73], v[162:165], v[208:211], v[70:73]
	v_mfma_f32_16x16x32_bf16 v[66:69], v[170:173], v[208:211], v[66:69]
	v_mfma_f32_16x16x32_bf16 v[120:123], v[166:169], v[182:185], v[120:123]
	v_mfma_f32_16x16x32_bf16 v[116:119], v[174:177], v[182:185], v[116:119]
	v_mfma_f32_16x16x32_bf16 v[104:107], v[166:169], v[190:193], v[104:107]
	v_mfma_f32_16x16x32_bf16 v[100:103], v[174:177], v[190:193], v[100:103]
	v_mfma_f32_16x16x32_bf16 v[86:89], v[166:169], v[204:207], v[86:89]
	v_mfma_f32_16x16x32_bf16 v[82:85], v[174:177], v[204:207], v[82:85]
	v_mfma_f32_16x16x32_bf16 v[70:73], v[166:169], v[214:217], v[70:73]
	v_mfma_f32_16x16x32_bf16 v[66:69], v[174:177], v[214:217], v[66:69]
	s_setprio 0
	s_barrier
	s_add_i32 s57, s57, s2
	v_lshl_add_u64 v[198:199], s[50:51], 0, v[136:137]
	s_mov_b32 m0, s57
	ds_read_b128 v[178:181], v145 offset:16384
	ds_read_b128 v[182:185], v145 offset:17408
	ds_read_b128 v[186:189], v145 offset:18432
	ds_read_b128 v[190:193], v145 offset:19456
	ds_read_b128 v[194:197], v145 offset:20480
	ds_read_b128 v[204:207], v145 offset:21504
	ds_read_b128 v[208:211], v145 offset:22528
	ds_read_b128 v[214:217], v145 offset:23552
	s_setprio 1
	global_load_lds_dwordx4 v[198:199], off
	s_add_i32 m0, s57, 0x2000
	s_add_u32 s58, s50, 0x20000
	v_lshl_add_u64 v[218:219], s[50:51], 0, v[132:133]
	s_addc_u32 s59, s51, 0
	s_add_i32 s57, s60, s2
	global_load_lds_dwordx4 v[218:219], off
	v_lshl_add_u64 v[220:221], s[58:59], 0, v[136:137]
	s_mov_b32 m0, s57
	v_lshl_add_u64 v[222:223], s[52:53], 0, v[134:135]
	global_load_lds_dwordx4 v[220:221], off
	v_lshl_add_u64 v[220:221], s[58:59], 0, v[132:133]
	s_add_i32 m0, s57, 0x2000
	s_nop 0
	global_load_lds_dwordx4 v[220:221], off
	v_lshl_add_u64 v[220:221], s[52:53], 0, v[138:139]
	s_mov_b32 m0, s4
	s_nop 0
	global_load_lds_dwordx4 v[220:221], off
	s_mov_b32 m0, s7
	s_nop 0
	global_load_lds_dwordx4 v[222:223], off
	s_waitcnt vmcnt(8)
	s_waitcnt lgkmcnt(0)
	s_barrier
	v_mfma_f32_16x16x32_bf16 v[62:65], v[146:149], v[178:181], v[62:65]
	v_mfma_f32_16x16x32_bf16 v[58:61], v[154:157], v[178:181], v[58:61]
	v_mfma_f32_16x16x32_bf16 v[46:49], v[146:149], v[186:189], v[46:49]
	v_mfma_f32_16x16x32_bf16 v[42:45], v[154:157], v[186:189], v[42:45]
	v_mfma_f32_16x16x32_bf16 v[30:33], v[146:149], v[194:197], v[30:33]
	v_mfma_f32_16x16x32_bf16 v[26:29], v[154:157], v[194:197], v[26:29]
	v_mfma_f32_16x16x32_bf16 v[14:17], v[146:149], v[208:211], v[14:17]
	v_mfma_f32_16x16x32_bf16 v[10:13], v[154:157], v[208:211], v[10:13]
	v_mfma_f32_16x16x32_bf16 v[62:65], v[150:153], v[182:185], v[62:65]
	v_mfma_f32_16x16x32_bf16 v[58:61], v[158:161], v[182:185], v[58:61]
	v_mfma_f32_16x16x32_bf16 v[46:49], v[150:153], v[190:193], v[46:49]
	v_mfma_f32_16x16x32_bf16 v[42:45], v[158:161], v[190:193], v[42:45]
	v_mfma_f32_16x16x32_bf16 v[30:33], v[150:153], v[204:207], v[30:33]
	v_mfma_f32_16x16x32_bf16 v[26:29], v[158:161], v[204:207], v[26:29]
	v_mfma_f32_16x16x32_bf16 v[14:17], v[150:153], v[214:217], v[14:17]
	v_mfma_f32_16x16x32_bf16 v[10:13], v[158:161], v[214:217], v[10:13]
	s_setprio 0
	s_setprio 1
	v_mfma_f32_16x16x32_bf16 v[54:57], v[162:165], v[178:181], v[54:57]
	v_mfma_f32_16x16x32_bf16 v[50:53], v[170:173], v[178:181], v[50:53]
	v_mfma_f32_16x16x32_bf16 v[38:41], v[162:165], v[186:189], v[38:41]
	v_mfma_f32_16x16x32_bf16 v[34:37], v[170:173], v[186:189], v[34:37]
	v_mfma_f32_16x16x32_bf16 v[22:25], v[162:165], v[194:197], v[22:25]
	v_mfma_f32_16x16x32_bf16 v[18:21], v[170:173], v[194:197], v[18:21]
	v_mfma_f32_16x16x32_bf16 v[6:9], v[162:165], v[208:211], v[6:9]
	v_mfma_f32_16x16x32_bf16 v[2:5], v[170:173], v[208:211], v[2:5]
	v_mfma_f32_16x16x32_bf16 v[54:57], v[166:169], v[182:185], v[54:57]
	v_mfma_f32_16x16x32_bf16 v[50:53], v[174:177], v[182:185], v[50:53]
	v_mfma_f32_16x16x32_bf16 v[38:41], v[166:169], v[190:193], v[38:41]
	v_mfma_f32_16x16x32_bf16 v[34:37], v[174:177], v[190:193], v[34:37]
	v_mfma_f32_16x16x32_bf16 v[22:25], v[166:169], v[204:207], v[22:25]
	v_mfma_f32_16x16x32_bf16 v[18:21], v[174:177], v[204:207], v[18:21]
	v_mfma_f32_16x16x32_bf16 v[6:9], v[166:169], v[214:217], v[6:9]
	v_mfma_f32_16x16x32_bf16 v[2:5], v[174:177], v[214:217], v[2:5]
	s_setprio 0
	s_barrier
	s_add_i32 s57, 0, 0x18000
	v_add_u32_e32 v98, s57, v144
	s_add_i32 s58, 0, 0x1c000
	ds_read_b128 v[146:149], v98
	ds_read_b128 v[150:153], v98 offset:1024
	ds_read_b128 v[154:157], v98 offset:2048
	ds_read_b128 v[158:161], v98 offset:3072
	v_add_u32_e32 v98, s58, v144
	ds_read_b128 v[162:165], v98
	ds_read_b128 v[166:169], v98 offset:1024
	ds_read_b128 v[170:173], v98 offset:2048
	ds_read_b128 v[174:177], v98 offset:3072
	s_add_u32 s52, s52, 0x20000
	s_addc_u32 s53, s53, 0
	s_mov_b32 m0, s8
	v_lshl_add_u64 v[224:225], s[52:53], 0, v[138:139]
	ds_read_b128 v[178:181], v145 offset:32768
	ds_read_b128 v[182:185], v145 offset:33792
	ds_read_b128 v[186:189], v145 offset:34816
	ds_read_b128 v[190:193], v145 offset:35840
	ds_read_b128 v[194:197], v145 offset:36864
	ds_read_b128 v[204:207], v145 offset:37888
	ds_read_b128 v[208:211], v145 offset:38912
	ds_read_b128 v[214:217], v145 offset:39936
	s_setprio 1
	global_load_lds_dwordx4 v[224:225], off
	v_lshl_add_u64 v[224:225], s[52:53], 0, v[134:135]
	s_mov_b32 m0, s9
	s_nop 0
	global_load_lds_dwordx4 v[224:225], off
	s_waitcnt vmcnt(8)
	s_waitcnt lgkmcnt(0)
	s_barrier
	v_mfma_f32_16x16x32_bf16 v[128:131], v[146:149], v[178:181], v[128:131]
	v_mfma_f32_16x16x32_bf16 v[124:127], v[154:157], v[178:181], v[124:127]
	v_mfma_f32_16x16x32_bf16 v[112:115], v[146:149], v[186:189], v[112:115]
	v_mfma_f32_16x16x32_bf16 v[108:111], v[154:157], v[186:189], v[108:111]
	v_mfma_f32_16x16x32_bf16 v[94:97], v[146:149], v[194:197], v[94:97]
	v_mfma_f32_16x16x32_bf16 v[90:93], v[154:157], v[194:197], v[90:93]
	v_mfma_f32_16x16x32_bf16 v[78:81], v[146:149], v[208:211], v[78:81]
	v_mfma_f32_16x16x32_bf16 v[74:77], v[154:157], v[208:211], v[74:77]
	v_mfma_f32_16x16x32_bf16 v[128:131], v[150:153], v[182:185], v[128:131]
	v_mfma_f32_16x16x32_bf16 v[124:127], v[158:161], v[182:185], v[124:127]
	v_mfma_f32_16x16x32_bf16 v[112:115], v[150:153], v[190:193], v[112:115]
	v_mfma_f32_16x16x32_bf16 v[108:111], v[158:161], v[190:193], v[108:111]
	v_mfma_f32_16x16x32_bf16 v[94:97], v[150:153], v[204:207], v[94:97]
	v_mfma_f32_16x16x32_bf16 v[90:93], v[158:161], v[204:207], v[90:93]
	v_mfma_f32_16x16x32_bf16 v[78:81], v[150:153], v[214:217], v[78:81]
	v_mfma_f32_16x16x32_bf16 v[74:77], v[158:161], v[214:217], v[74:77]
	s_setprio 0
	s_setprio 1
	v_mfma_f32_16x16x32_bf16 v[120:123], v[162:165], v[178:181], v[120:123]
	v_mfma_f32_16x16x32_bf16 v[116:119], v[170:173], v[178:181], v[116:119]
	v_mfma_f32_16x16x32_bf16 v[104:107], v[162:165], v[186:189], v[104:107]
	v_mfma_f32_16x16x32_bf16 v[100:103], v[170:173], v[186:189], v[100:103]
	v_mfma_f32_16x16x32_bf16 v[86:89], v[162:165], v[194:197], v[86:89]
	v_mfma_f32_16x16x32_bf16 v[82:85], v[170:173], v[194:197], v[82:85]
	v_mfma_f32_16x16x32_bf16 v[70:73], v[162:165], v[208:211], v[70:73]
	v_mfma_f32_16x16x32_bf16 v[66:69], v[170:173], v[208:211], v[66:69]
	v_mfma_f32_16x16x32_bf16 v[120:123], v[166:169], v[182:185], v[120:123]
	v_mfma_f32_16x16x32_bf16 v[116:119], v[174:177], v[182:185], v[116:119]
	v_mfma_f32_16x16x32_bf16 v[104:107], v[166:169], v[190:193], v[104:107]
	v_mfma_f32_16x16x32_bf16 v[100:103], v[174:177], v[190:193], v[100:103]
	v_mfma_f32_16x16x32_bf16 v[86:89], v[166:169], v[204:207], v[86:89]
	v_mfma_f32_16x16x32_bf16 v[82:85], v[174:177], v[204:207], v[82:85]
	v_mfma_f32_16x16x32_bf16 v[70:73], v[166:169], v[214:217], v[70:73]
	v_mfma_f32_16x16x32_bf16 v[66:69], v[174:177], v[214:217], v[66:69]
	s_setprio 0
	s_barrier
	s_add_i32 s52, s57, s2
	v_lshl_add_u64 v[198:199], v[198:199], 0, s[28:29]
	s_mov_b32 m0, s52
	ds_read_b128 v[178:181], v145 offset:49152
	ds_read_b128 v[182:185], v145 offset:50176
	ds_read_b128 v[186:189], v145 offset:51200
	ds_read_b128 v[190:193], v145 offset:52224
	ds_read_b128 v[194:197], v145 offset:53248
	ds_read_b128 v[204:207], v145 offset:54272
	ds_read_b128 v[208:211], v145 offset:55296
	ds_read_b128 v[214:217], v145 offset:56320
	s_setprio 1
	global_load_lds_dwordx4 v[198:199], off
	s_add_i32 m0, s52, 0x2000
	s_add_u32 s50, s50, 0x20080
	v_lshl_add_u64 v[198:199], v[218:219], 0, s[28:29]
	s_addc_u32 s51, s51, 0
	s_add_i32 s52, s58, s2
	global_load_lds_dwordx4 v[198:199], off
	v_lshl_add_u64 v[198:199], s[50:51], 0, v[136:137]
	s_mov_b32 m0, s52
	s_nop 0
	global_load_lds_dwordx4 v[198:199], off
	v_lshl_add_u64 v[198:199], s[50:51], 0, v[132:133]
	s_add_i32 m0, s52, 0x2000
	s_nop 0
	global_load_lds_dwordx4 v[198:199], off
	v_lshl_add_u64 v[198:199], v[220:221], 0, s[28:29]
	s_mov_b32 m0, s12
	s_nop 0
	global_load_lds_dwordx4 v[198:199], off
	v_lshl_add_u64 v[198:199], v[222:223], 0, s[28:29]
	s_mov_b32 m0, s13
	s_nop 0
	global_load_lds_dwordx4 v[198:199], off
	s_waitcnt vmcnt(8)
	s_waitcnt lgkmcnt(0)
	s_barrier
	v_mfma_f32_16x16x32_bf16 v[62:65], v[146:149], v[178:181], v[62:65]
	v_mfma_f32_16x16x32_bf16 v[58:61], v[154:157], v[178:181], v[58:61]
	v_mfma_f32_16x16x32_bf16 v[46:49], v[146:149], v[186:189], v[46:49]
	v_mfma_f32_16x16x32_bf16 v[42:45], v[154:157], v[186:189], v[42:45]
	v_mfma_f32_16x16x32_bf16 v[30:33], v[146:149], v[194:197], v[30:33]
	v_mfma_f32_16x16x32_bf16 v[26:29], v[154:157], v[194:197], v[26:29]
	v_mfma_f32_16x16x32_bf16 v[14:17], v[146:149], v[208:211], v[14:17]
	v_mfma_f32_16x16x32_bf16 v[10:13], v[154:157], v[208:211], v[10:13]
	v_mfma_f32_16x16x32_bf16 v[62:65], v[150:153], v[182:185], v[62:65]
	v_mfma_f32_16x16x32_bf16 v[58:61], v[158:161], v[182:185], v[58:61]
	v_mfma_f32_16x16x32_bf16 v[46:49], v[150:153], v[190:193], v[46:49]
	v_mfma_f32_16x16x32_bf16 v[42:45], v[158:161], v[190:193], v[42:45]
	v_mfma_f32_16x16x32_bf16 v[30:33], v[150:153], v[204:207], v[30:33]
	v_mfma_f32_16x16x32_bf16 v[26:29], v[158:161], v[204:207], v[26:29]
	v_mfma_f32_16x16x32_bf16 v[14:17], v[150:153], v[214:217], v[14:17]
	v_mfma_f32_16x16x32_bf16 v[10:13], v[158:161], v[214:217], v[10:13]
	s_setprio 0
	s_setprio 1
	v_mfma_f32_16x16x32_bf16 v[54:57], v[162:165], v[178:181], v[54:57]
	v_mfma_f32_16x16x32_bf16 v[50:53], v[170:173], v[178:181], v[50:53]
	v_mfma_f32_16x16x32_bf16 v[38:41], v[162:165], v[186:189], v[38:41]
	v_mfma_f32_16x16x32_bf16 v[34:37], v[170:173], v[186:189], v[34:37]
	v_mfma_f32_16x16x32_bf16 v[22:25], v[162:165], v[194:197], v[22:25]
	v_mfma_f32_16x16x32_bf16 v[18:21], v[170:173], v[194:197], v[18:21]
	v_mfma_f32_16x16x32_bf16 v[6:9], v[162:165], v[208:211], v[6:9]
	v_mfma_f32_16x16x32_bf16 v[2:5], v[170:173], v[208:211], v[2:5]
	v_mfma_f32_16x16x32_bf16 v[54:57], v[166:169], v[182:185], v[54:57]
	v_mfma_f32_16x16x32_bf16 v[50:53], v[174:177], v[182:185], v[50:53]
	v_mfma_f32_16x16x32_bf16 v[38:41], v[166:169], v[190:193], v[38:41]
	v_mfma_f32_16x16x32_bf16 v[34:37], v[174:177], v[190:193], v[34:37]
	v_mfma_f32_16x16x32_bf16 v[22:25], v[166:169], v[204:207], v[22:25]
	v_mfma_f32_16x16x32_bf16 v[18:21], v[174:177], v[204:207], v[18:21]
	v_mfma_f32_16x16x32_bf16 v[6:9], v[166:169], v[214:217], v[6:9]
	v_mfma_f32_16x16x32_bf16 v[2:5], v[174:177], v[214:217], v[2:5]
	s_setprio 0
	s_barrier
	s_add_i32 s56, s56, 2
	s_add_u32 s48, s48, 0x100
	s_addc_u32 s49, s49, 0
	s_add_u32 s54, s54, 0x100
	s_addc_u32 s55, s55, 0
	s_cmp_gt_u32 s56, 5
	s_cbranch_scc0 .LBB0_893
	s_and_b64 vcc, exec, s[22:23]
	s_cbranch_vccz .LBB0_896
	s_barrier

.LBB0_1072:
	s_add_u32 s60, s56, s58
	s_addc_u32 s61, s57, s59
	s_add_u32 s60, s60, 0x100
	s_addc_u32 s61, s61, 0
	s_add_u32 s71, s66, s58
	s_addc_u32 s72, s67, s59
	s_add_i32 s73, 0, 0x10000
	s_cmpk_eq_i32 s58, 0x700
	s_cselect_b32 s63, s45, s61
	s_cselect_b32 s62, s51, s60
	v_add_u32_e32 v98, s73, v214
	s_cselect_b32 s61, s49, s72
	s_cselect_b32 s60, s65, s71
	s_add_i32 s71, 0, 0x14000
	ds_read_b128 v[138:141], v98
	ds_read_b128 v[142:145], v98 offset:1024
	ds_read_b128 v[146:149], v98 offset:2048
	ds_read_b128 v[150:153], v98 offset:3072
	v_add_u32_e32 v98, s71, v214
	ds_read_b128 v[154:157], v98
	ds_read_b128 v[158:161], v98 offset:1024
	ds_read_b128 v[162:165], v98 offset:2048
	ds_read_b128 v[166:169], v98 offset:3072
	v_lshl_add_u64 v[100:101], v[134:135], 0, s[58:59]
	s_add_i32 m0, s9, 0xc000
	ds_read_b128 v[170:173], v218
	ds_read_b128 v[186:189], v218 offset:1024
	ds_read_b128 v[190:193], v218 offset:2048
	ds_read_b128 v[194:197], v218 offset:3072
	ds_read_b128 v[204:207], v218 offset:4096
	ds_read_b128 v[208:211], v218 offset:5120
	ds_read_b128 v[220:223], v218 offset:6144
	ds_read_b128 v[224:227], v218 offset:7168
	s_setprio 1
	global_load_lds_dwordx4 v[100:101], off
	v_lshl_add_u64 v[100:101], v[136:137], 0, s[58:59]
	s_add_i32 m0, s9, 0xe000
	s_nop 0
	global_load_lds_dwordx4 v[100:101], off
	s_waitcnt vmcnt(8)
	s_waitcnt lgkmcnt(0)
	s_barrier
	v_mfma_f32_16x16x32_bf16 v[130:133], v[138:141], v[170:173], v[130:133]
	v_mfma_f32_16x16x32_bf16 v[126:129], v[146:149], v[170:173], v[126:129]
	v_mfma_f32_16x16x32_bf16 v[122:125], v[138:141], v[190:193], v[122:125]
	v_mfma_f32_16x16x32_bf16 v[118:121], v[146:149], v[190:193], v[118:121]
	v_mfma_f32_16x16x32_bf16 v[114:117], v[138:141], v[204:207], v[114:117]
	v_mfma_f32_16x16x32_bf16 v[110:113], v[146:149], v[204:207], v[110:113]
	v_mfma_f32_16x16x32_bf16 v[106:109], v[138:141], v[220:223], v[106:109]
	v_mfma_f32_16x16x32_bf16 v[100:103], v[146:149], v[220:223], v[102:105]
	v_mfma_f32_16x16x32_bf16 v[130:133], v[142:145], v[186:189], v[130:133]
	v_mfma_f32_16x16x32_bf16 v[126:129], v[150:153], v[186:189], v[126:129]
	v_mfma_f32_16x16x32_bf16 v[122:125], v[142:145], v[194:197], v[122:125]
	v_mfma_f32_16x16x32_bf16 v[118:121], v[150:153], v[194:197], v[118:121]
	v_mfma_f32_16x16x32_bf16 v[114:117], v[142:145], v[208:211], v[114:117]
	v_mfma_f32_16x16x32_bf16 v[110:113], v[150:153], v[208:211], v[110:113]
	v_mfma_f32_16x16x32_bf16 v[106:109], v[142:145], v[224:227], v[106:109]
	v_mfma_f32_16x16x32_bf16 v[100:103], v[150:153], v[224:227], v[100:103]
	s_setprio 0
	s_setprio 1
	v_mfma_f32_16x16x32_bf16 v[62:65], v[154:157], v[170:173], v[62:65]
	v_mfma_f32_16x16x32_bf16 v[58:61], v[162:165], v[170:173], v[58:61]
	v_mfma_f32_16x16x32_bf16 v[54:57], v[154:157], v[190:193], v[54:57]
	v_mfma_f32_16x16x32_bf16 v[50:53], v[162:165], v[190:193], v[50:53]
	v_mfma_f32_16x16x32_bf16 v[46:49], v[154:157], v[204:207], v[46:49]
	v_mfma_f32_16x16x32_bf16 v[42:45], v[162:165], v[204:207], v[42:45]
	v_mfma_f32_16x16x32_bf16 v[38:41], v[154:157], v[220:223], v[38:41]
	v_mfma_f32_16x16x32_bf16 v[34:37], v[162:165], v[220:223], v[34:37]
	v_mfma_f32_16x16x32_bf16 v[62:65], v[158:161], v[186:189], v[62:65]
	v_mfma_f32_16x16x32_bf16 v[58:61], v[166:169], v[186:189], v[58:61]
	v_mfma_f32_16x16x32_bf16 v[54:57], v[158:161], v[194:197], v[54:57]
	v_mfma_f32_16x16x32_bf16 v[50:53], v[166:169], v[194:197], v[50:53]
	v_mfma_f32_16x16x32_bf16 v[46:49], v[158:161], v[208:211], v[46:49]
	v_mfma_f32_16x16x32_bf16 v[42:45], v[166:169], v[208:211], v[42:45]
	v_mfma_f32_16x16x32_bf16 v[38:41], v[158:161], v[224:227], v[38:41]
	v_mfma_f32_16x16x32_bf16 v[34:37], v[166:169], v[224:227], v[34:37]
	s_setprio 0
	s_barrier
	s_add_i32 s72, s73, s4
	v_lshl_add_u64 v[198:199], s[60:61], 0, v[176:177]
	s_mov_b32 m0, s72
	ds_read_b128 v[170:173], v218 offset:16384
	ds_read_b128 v[186:189], v218 offset:17408
	ds_read_b128 v[190:193], v218 offset:18432
	ds_read_b128 v[194:197], v218 offset:19456
	ds_read_b128 v[204:207], v218 offset:20480
	ds_read_b128 v[208:211], v218 offset:21504
	ds_read_b128 v[220:223], v218 offset:22528
	ds_read_b128 v[224:227], v218 offset:23552
	s_setprio 1
	global_load_lds_dwordx4 v[198:199], off
	s_add_i32 m0, s72, 0x2000
	s_add_u32 s72, s60, 0x40000
	v_lshl_add_u64 v[228:229], s[60:61], 0, v[180:181]
	s_addc_u32 s73, s61, 0
	s_add_i32 s71, s71, s4
	global_load_lds_dwordx4 v[228:229], off
	v_lshl_add_u64 v[104:105], s[72:73], 0, v[176:177]
	s_mov_b32 m0, s71
	v_lshl_add_u64 v[230:231], s[62:63], 0, v[174:175]
	global_load_lds_dwordx4 v[104:105], off
	v_lshl_add_u64 v[104:105], s[72:73], 0, v[180:181]
	s_add_i32 m0, s71, 0x2000
	v_lshl_add_u64 v[232:233], s[62:63], 0, v[178:179]
	global_load_lds_dwordx4 v[104:105], off
	s_mov_b32 m0, s9
	s_nop 0
	global_load_lds_dwordx4 v[230:231], off
	s_mov_b32 m0, s10
	s_nop 0
	global_load_lds_dwordx4 v[232:233], off
	s_waitcnt vmcnt(8)
	s_waitcnt lgkmcnt(0)
	s_barrier
	v_mfma_f32_16x16x32_bf16 v[94:97], v[138:141], v[170:173], v[94:97]
	v_mfma_f32_16x16x32_bf16 v[90:93], v[146:149], v[170:173], v[90:93]
	v_mfma_f32_16x16x32_bf16 v[86:89], v[138:141], v[190:193], v[86:89]
	v_mfma_f32_16x16x32_bf16 v[82:85], v[146:149], v[190:193], v[82:85]
	v_mfma_f32_16x16x32_bf16 v[78:81], v[138:141], v[204:207], v[78:81]
	v_mfma_f32_16x16x32_bf16 v[74:77], v[146:149], v[204:207], v[74:77]
	v_mfma_f32_16x16x32_bf16 v[70:73], v[138:141], v[220:223], v[70:73]
	v_mfma_f32_16x16x32_bf16 v[66:69], v[146:149], v[220:223], v[66:69]
	v_mfma_f32_16x16x32_bf16 v[94:97], v[142:145], v[186:189], v[94:97]
	v_mfma_f32_16x16x32_bf16 v[90:93], v[150:153], v[186:189], v[90:93]
	v_mfma_f32_16x16x32_bf16 v[86:89], v[142:145], v[194:197], v[86:89]
	v_mfma_f32_16x16x32_bf16 v[82:85], v[150:153], v[194:197], v[82:85]
	v_mfma_f32_16x16x32_bf16 v[78:81], v[142:145], v[208:211], v[78:81]
	v_mfma_f32_16x16x32_bf16 v[74:77], v[150:153], v[208:211], v[74:77]
	v_mfma_f32_16x16x32_bf16 v[70:73], v[142:145], v[224:227], v[70:73]
	v_mfma_f32_16x16x32_bf16 v[66:69], v[150:153], v[224:227], v[66:69]
	s_setprio 0
	s_setprio 1
	v_mfma_f32_16x16x32_bf16 v[30:33], v[154:157], v[170:173], v[30:33]
	v_mfma_f32_16x16x32_bf16 v[26:29], v[162:165], v[170:173], v[26:29]
	v_mfma_f32_16x16x32_bf16 v[22:25], v[154:157], v[190:193], v[22:25]
	v_mfma_f32_16x16x32_bf16 v[18:21], v[162:165], v[190:193], v[18:21]
	v_mfma_f32_16x16x32_bf16 v[14:17], v[154:157], v[204:207], v[14:17]
	v_mfma_f32_16x16x32_bf16 v[10:13], v[162:165], v[204:207], v[10:13]
	v_mfma_f32_16x16x32_bf16 v[6:9], v[154:157], v[220:223], v[6:9]
	v_mfma_f32_16x16x32_bf16 v[2:5], v[162:165], v[220:223], v[2:5]
	v_mfma_f32_16x16x32_bf16 v[30:33], v[158:161], v[186:189], v[30:33]
	v_mfma_f32_16x16x32_bf16 v[26:29], v[166:169], v[186:189], v[26:29]
	v_mfma_f32_16x16x32_bf16 v[22:25], v[158:161], v[194:197], v[22:25]
	v_mfma_f32_16x16x32_bf16 v[18:21], v[166:169], v[194:197], v[18:21]
	v_mfma_f32_16x16x32_bf16 v[14:17], v[158:161], v[208:211], v[14:17]
	v_mfma_f32_16x16x32_bf16 v[10:13], v[166:169], v[208:211], v[10:13]
	v_mfma_f32_16x16x32_bf16 v[6:9], v[158:161], v[224:227], v[6:9]
	v_mfma_f32_16x16x32_bf16 v[2:5], v[166:169], v[224:227], v[2:5]
	s_setprio 0
	s_barrier
	s_add_i32 s71, 0, 0x18000
	v_add_u32_e32 v98, s71, v214
	s_add_i32 s72, 0, 0x1c000
	ds_read_b128 v[138:141], v98
	ds_read_b128 v[142:145], v98 offset:1024
	ds_read_b128 v[146:149], v98 offset:2048
	ds_read_b128 v[150:153], v98 offset:3072
	v_add_u32_e32 v98, s72, v214
	ds_read_b128 v[154:157], v98
	ds_read_b128 v[158:161], v98 offset:1024
	ds_read_b128 v[162:165], v98 offset:2048
	ds_read_b128 v[166:169], v98 offset:3072
	s_add_u32 s62, s62, 0x40000
	s_addc_u32 s63, s63, 0
	s_mov_b32 m0, s11
	v_lshl_add_u64 v[104:105], s[62:63], 0, v[174:175]
	ds_read_b128 v[170:173], v218 offset:32768
	ds_read_b128 v[186:189], v218 offset:33792
	ds_read_b128 v[190:193], v218 offset:34816
	ds_read_b128 v[194:197], v218 offset:35840
	ds_read_b128 v[204:207], v218 offset:36864
	ds_read_b128 v[208:211], v218 offset:37888
	ds_read_b128 v[220:223], v218 offset:38912
	ds_read_b128 v[224:227], v218 offset:39936
	s_setprio 1
	global_load_lds_dwordx4 v[104:105], off
	v_lshl_add_u64 v[104:105], s[62:63], 0, v[178:179]
	s_mov_b32 m0, s12
	s_nop 0
	global_load_lds_dwordx4 v[104:105], off
	s_waitcnt vmcnt(8)
	s_waitcnt lgkmcnt(0)
	s_barrier
	v_mfma_f32_16x16x32_bf16 v[130:133], v[138:141], v[170:173], v[130:133]
	v_mfma_f32_16x16x32_bf16 v[126:129], v[146:149], v[170:173], v[126:129]
	v_mfma_f32_16x16x32_bf16 v[122:125], v[138:141], v[190:193], v[122:125]
	v_mfma_f32_16x16x32_bf16 v[118:121], v[146:149], v[190:193], v[118:121]
	v_mfma_f32_16x16x32_bf16 v[114:117], v[138:141], v[204:207], v[114:117]
	v_mfma_f32_16x16x32_bf16 v[110:113], v[146:149], v[204:207], v[110:113]
	v_mfma_f32_16x16x32_bf16 v[104:107], v[138:141], v[220:223], v[106:109]
	v_mfma_f32_16x16x32_bf16 v[100:103], v[146:149], v[220:223], v[100:103]
	v_mfma_f32_16x16x32_bf16 v[130:133], v[142:145], v[186:189], v[130:133]
	v_mfma_f32_16x16x32_bf16 v[126:129], v[150:153], v[186:189], v[126:129]
	v_mfma_f32_16x16x32_bf16 v[122:125], v[142:145], v[194:197], v[122:125]
	v_mfma_f32_16x16x32_bf16 v[118:121], v[150:153], v[194:197], v[118:121]
	v_mfma_f32_16x16x32_bf16 v[114:117], v[142:145], v[208:211], v[114:117]
	v_mfma_f32_16x16x32_bf16 v[110:113], v[150:153], v[208:211], v[110:113]
	v_mfma_f32_16x16x32_bf16 v[106:109], v[142:145], v[224:227], v[104:107]
	v_mfma_f32_16x16x32_bf16 v[102:105], v[150:153], v[224:227], v[100:103]
	s_setprio 0
	s_setprio 1
	v_mfma_f32_16x16x32_bf16 v[62:65], v[154:157], v[170:173], v[62:65]
	v_mfma_f32_16x16x32_bf16 v[58:61], v[162:165], v[170:173], v[58:61]
	v_mfma_f32_16x16x32_bf16 v[54:57], v[154:157], v[190:193], v[54:57]
	v_mfma_f32_16x16x32_bf16 v[50:53], v[162:165], v[190:193], v[50:53]
	v_mfma_f32_16x16x32_bf16 v[46:49], v[154:157], v[204:207], v[46:49]
	v_mfma_f32_16x16x32_bf16 v[42:45], v[162:165], v[204:207], v[42:45]
	v_mfma_f32_16x16x32_bf16 v[38:41], v[154:157], v[220:223], v[38:41]
	v_mfma_f32_16x16x32_bf16 v[34:37], v[162:165], v[220:223], v[34:37]
	v_mfma_f32_16x16x32_bf16 v[62:65], v[158:161], v[186:189], v[62:65]
	v_mfma_f32_16x16x32_bf16 v[58:61], v[166:169], v[186:189], v[58:61]
	v_mfma_f32_16x16x32_bf16 v[54:57], v[158:161], v[194:197], v[54:57]
	v_mfma_f32_16x16x32_bf16 v[50:53], v[166:169], v[194:197], v[50:53]
	v_mfma_f32_16x16x32_bf16 v[46:49], v[158:161], v[208:211], v[46:49]
	v_mfma_f32_16x16x32_bf16 v[42:45], v[166:169], v[208:211], v[42:45]
	v_mfma_f32_16x16x32_bf16 v[38:41], v[158:161], v[224:227], v[38:41]
	v_mfma_f32_16x16x32_bf16 v[34:37], v[166:169], v[224:227], v[34:37]
	s_setprio 0
	s_barrier
	s_add_i32 s62, s71, s4
	v_lshl_add_u64 v[100:101], v[198:199], 0, s[28:29]
	s_mov_b32 m0, s62
	ds_read_b128 v[170:173], v218 offset:49152
	ds_read_b128 v[186:189], v218 offset:50176
	ds_read_b128 v[190:193], v218 offset:51200
	ds_read_b128 v[194:197], v218 offset:52224
	ds_read_b128 v[204:207], v218 offset:53248
	ds_read_b128 v[208:211], v218 offset:54272
	ds_read_b128 v[220:223], v218 offset:55296
	ds_read_b128 v[224:227], v218 offset:56320
	s_setprio 1
	global_load_lds_dwordx4 v[100:101], off
	s_add_i32 m0, s62, 0x2000
	s_add_u32 s60, s60, 0x40080
	v_lshl_add_u64 v[100:101], v[228:229], 0, s[28:29]
	s_addc_u32 s61, s61, 0
	s_add_i32 s62, s72, s4
	global_load_lds_dwordx4 v[100:101], off
	v_lshl_add_u64 v[100:101], s[60:61], 0, v[176:177]
	s_mov_b32 m0, s62
	s_nop 0
	global_load_lds_dwordx4 v[100:101], off
	v_lshl_add_u64 v[100:101], s[60:61], 0, v[180:181]
	s_add_i32 m0, s62, 0x2000
	s_nop 0
	global_load_lds_dwordx4 v[100:101], off
	v_lshl_add_u64 v[100:101], v[230:231], 0, s[28:29]
	s_mov_b32 m0, s15
	s_nop 0
	global_load_lds_dwordx4 v[100:101], off
	v_lshl_add_u64 v[100:101], v[232:233], 0, s[28:29]
	s_mov_b32 m0, s16
	s_nop 0
	global_load_lds_dwordx4 v[100:101], off
	s_waitcnt vmcnt(8)
	s_waitcnt lgkmcnt(0)
	s_barrier
	v_mfma_f32_16x16x32_bf16 v[94:97], v[138:141], v[170:173], v[94:97]
	v_mfma_f32_16x16x32_bf16 v[90:93], v[146:149], v[170:173], v[90:93]
	v_mfma_f32_16x16x32_bf16 v[86:89], v[138:141], v[190:193], v[86:89]
	v_mfma_f32_16x16x32_bf16 v[82:85], v[146:149], v[190:193], v[82:85]
	v_mfma_f32_16x16x32_bf16 v[78:81], v[138:141], v[204:207], v[78:81]
	v_mfma_f32_16x16x32_bf16 v[74:77], v[146:149], v[204:207], v[74:77]
	v_mfma_f32_16x16x32_bf16 v[70:73], v[138:141], v[220:223], v[70:73]
	v_mfma_f32_16x16x32_bf16 v[66:69], v[146:149], v[220:223], v[66:69]
	v_mfma_f32_16x16x32_bf16 v[94:97], v[142:145], v[186:189], v[94:97]
	v_mfma_f32_16x16x32_bf16 v[90:93], v[150:153], v[186:189], v[90:93]
	v_mfma_f32_16x16x32_bf16 v[86:89], v[142:145], v[194:197], v[86:89]
	v_mfma_f32_16x16x32_bf16 v[82:85], v[150:153], v[194:197], v[82:85]
	v_mfma_f32_16x16x32_bf16 v[78:81], v[142:145], v[208:211], v[78:81]
	v_mfma_f32_16x16x32_bf16 v[74:77], v[150:153], v[208:211], v[74:77]
	v_mfma_f32_16x16x32_bf16 v[70:73], v[142:145], v[224:227], v[70:73]
	v_mfma_f32_16x16x32_bf16 v[66:69], v[150:153], v[224:227], v[66:69]
	s_setprio 0
	s_setprio 1
	v_mfma_f32_16x16x32_bf16 v[30:33], v[154:157], v[170:173], v[30:33]
	v_mfma_f32_16x16x32_bf16 v[26:29], v[162:165], v[170:173], v[26:29]
	v_mfma_f32_16x16x32_bf16 v[22:25], v[154:157], v[190:193], v[22:25]
	v_mfma_f32_16x16x32_bf16 v[18:21], v[162:165], v[190:193], v[18:21]
	v_mfma_f32_16x16x32_bf16 v[14:17], v[154:157], v[204:207], v[14:17]
	v_mfma_f32_16x16x32_bf16 v[10:13], v[162:165], v[204:207], v[10:13]
	v_mfma_f32_16x16x32_bf16 v[6:9], v[154:157], v[220:223], v[6:9]
	v_mfma_f32_16x16x32_bf16 v[2:5], v[162:165], v[220:223], v[2:5]
	v_mfma_f32_16x16x32_bf16 v[30:33], v[158:161], v[186:189], v[30:33]
	v_mfma_f32_16x16x32_bf16 v[26:29], v[166:169], v[186:189], v[26:29]
	v_mfma_f32_16x16x32_bf16 v[22:25], v[158:161], v[194:197], v[22:25]
	v_mfma_f32_16x16x32_bf16 v[18:21], v[166:169], v[194:197], v[18:21]
	v_mfma_f32_16x16x32_bf16 v[14:17], v[158:161], v[208:211], v[14:17]
	v_mfma_f32_16x16x32_bf16 v[10:13], v[166:169], v[208:211], v[10:13]
	v_mfma_f32_16x16x32_bf16 v[6:9], v[158:161], v[224:227], v[6:9]
	v_mfma_f32_16x16x32_bf16 v[2:5], v[166:169], v[224:227], v[2:5]
	s_setprio 0
	s_barrier
	s_add_u32 s58, s58, 0x100
	s_addc_u32 s59, s59, 0
	s_cmp_gt_u32 s70, 13
	s_cbranch_scc1 .LBB0_1075

.LBB0_1110:
	s_add_i32 s75, s75, 2
	s_add_u32 s60, s38, s58
	s_addc_u32 s61, s39, s59
	s_add_u32 s60, s60, 0x100
	s_addc_u32 s61, s61, 0
	s_add_u32 s76, s72, s58
	s_addc_u32 s77, s73, s59
	s_add_i32 s78, 0, 0x10000
	s_cmp_eq_u32 s74, s58
	s_cselect_b32 s63, s49, s61
	s_cselect_b32 s62, s70, s60
	v_add_u32_e32 v98, s78, v177
	s_cselect_b32 s61, s45, s77
	s_cselect_b32 s60, s71, s76
	s_add_i32 s79, 0, 0x14000
	ds_read_b128 v[138:141], v98
	ds_read_b128 v[142:145], v98 offset:1024
	ds_read_b128 v[146:149], v98 offset:2048
	ds_read_b128 v[150:153], v98 offset:3072
	v_add_u32_e32 v98, s79, v177
	ds_read_b128 v[154:157], v98
	ds_read_b128 v[170:173], v98 offset:1024
	ds_read_b128 v[182:185], v98 offset:2048
	ds_read_b128 v[186:189], v98 offset:3072
	v_lshl_add_u64 v[100:101], v[134:135], 0, s[58:59]
	s_add_i32 m0, s10, 0xc000
	ds_read_b128 v[190:193], v181
	ds_read_b128 v[194:197], v181 offset:1024
	ds_read_b128 v[204:207], v181 offset:2048
	ds_read_b128 v[208:211], v181 offset:3072
	ds_read_b128 v[214:217], v181 offset:4096
	ds_read_b128 v[218:221], v181 offset:5120
	ds_read_b128 v[222:225], v181 offset:6144
	ds_read_b128 v[226:229], v181 offset:7168
	s_setprio 1
	global_load_lds_dwordx4 v[100:101], off
	v_lshl_add_u64 v[100:101], v[136:137], 0, s[58:59]
	s_add_i32 m0, s10, 0xe000
	s_nop 0
	global_load_lds_dwordx4 v[100:101], off
	s_waitcnt vmcnt(8)
	s_waitcnt lgkmcnt(0)
	s_barrier
	v_mfma_f32_16x16x32_bf16 v[130:133], v[138:141], v[190:193], v[130:133]
	v_mfma_f32_16x16x32_bf16 v[126:129], v[146:149], v[190:193], v[126:129]
	v_mfma_f32_16x16x32_bf16 v[114:117], v[138:141], v[204:207], v[114:117]
	v_mfma_f32_16x16x32_bf16 v[110:113], v[146:149], v[204:207], v[110:113]
	v_mfma_f32_16x16x32_bf16 v[94:97], v[138:141], v[214:217], v[94:97]
	v_mfma_f32_16x16x32_bf16 v[90:93], v[146:149], v[214:217], v[90:93]
	v_mfma_f32_16x16x32_bf16 v[78:81], v[138:141], v[222:225], v[78:81]
	v_mfma_f32_16x16x32_bf16 v[74:77], v[146:149], v[222:225], v[74:77]
	v_mfma_f32_16x16x32_bf16 v[130:133], v[142:145], v[194:197], v[130:133]
	v_mfma_f32_16x16x32_bf16 v[126:129], v[150:153], v[194:197], v[126:129]
	v_mfma_f32_16x16x32_bf16 v[114:117], v[142:145], v[208:211], v[114:117]
	v_mfma_f32_16x16x32_bf16 v[110:113], v[150:153], v[208:211], v[110:113]
	v_mfma_f32_16x16x32_bf16 v[94:97], v[142:145], v[218:221], v[94:97]
	v_mfma_f32_16x16x32_bf16 v[90:93], v[150:153], v[218:221], v[90:93]
	v_mfma_f32_16x16x32_bf16 v[78:81], v[142:145], v[226:229], v[78:81]
	v_mfma_f32_16x16x32_bf16 v[74:77], v[150:153], v[226:229], v[74:77]
	s_setprio 0
	s_setprio 1
	v_mfma_f32_16x16x32_bf16 v[122:125], v[154:157], v[190:193], v[122:125]
	v_mfma_f32_16x16x32_bf16 v[118:121], v[182:185], v[190:193], v[118:121]
	v_mfma_f32_16x16x32_bf16 v[106:109], v[154:157], v[204:207], v[106:109]
	v_mfma_f32_16x16x32_bf16 v[100:103], v[182:185], v[204:207], v[102:105]
	v_mfma_f32_16x16x32_bf16 v[86:89], v[154:157], v[214:217], v[86:89]
	v_mfma_f32_16x16x32_bf16 v[82:85], v[182:185], v[214:217], v[82:85]
	v_mfma_f32_16x16x32_bf16 v[70:73], v[154:157], v[222:225], v[70:73]
	v_mfma_f32_16x16x32_bf16 v[66:69], v[182:185], v[222:225], v[66:69]
	v_mfma_f32_16x16x32_bf16 v[122:125], v[170:173], v[194:197], v[122:125]
	v_mfma_f32_16x16x32_bf16 v[118:121], v[186:189], v[194:197], v[118:121]
	v_mfma_f32_16x16x32_bf16 v[106:109], v[170:173], v[208:211], v[106:109]
	v_mfma_f32_16x16x32_bf16 v[100:103], v[186:189], v[208:211], v[100:103]
	v_mfma_f32_16x16x32_bf16 v[86:89], v[170:173], v[218:221], v[86:89]
	v_mfma_f32_16x16x32_bf16 v[82:85], v[186:189], v[218:221], v[82:85]
	v_mfma_f32_16x16x32_bf16 v[70:73], v[170:173], v[226:229], v[70:73]
	v_mfma_f32_16x16x32_bf16 v[66:69], v[186:189], v[226:229], v[66:69]
	s_setprio 0
	s_barrier
	s_add_i32 s76, s78, s9
	v_lshl_add_u64 v[174:175], s[60:61], 0, v[162:163]
	s_mov_b32 m0, s76
	ds_read_b128 v[190:193], v181 offset:16384
	ds_read_b128 v[194:197], v181 offset:17408
	ds_read_b128 v[204:207], v181 offset:18432
	ds_read_b128 v[208:211], v181 offset:19456
	ds_read_b128 v[214:217], v181 offset:20480
	ds_read_b128 v[218:221], v181 offset:21504
	ds_read_b128 v[222:225], v181 offset:22528
	ds_read_b128 v[226:229], v181 offset:23552
	s_setprio 1
	global_load_lds_dwordx4 v[174:175], off
	s_add_i32 m0, s76, 0x2000
	s_add_u32 s76, s60, 0x40000
	v_lshl_add_u64 v[198:199], s[60:61], 0, v[158:159]
	s_addc_u32 s77, s61, 0
	s_add_i32 s78, s79, s9
	global_load_lds_dwordx4 v[198:199], off
	v_lshl_add_u64 v[104:105], s[76:77], 0, v[162:163]
	s_mov_b32 m0, s78
	v_lshl_add_u64 v[230:231], s[62:63], 0, v[164:165]
	global_load_lds_dwordx4 v[104:105], off
	v_lshl_add_u64 v[104:105], s[76:77], 0, v[158:159]
	s_add_i32 m0, s78, 0x2000
	v_lshl_add_u64 v[232:233], s[62:63], 0, v[160:161]
	global_load_lds_dwordx4 v[104:105], off
	s_mov_b32 m0, s10
	s_nop 0
	global_load_lds_dwordx4 v[230:231], off
	s_mov_b32 m0, s11
	s_nop 0
	global_load_lds_dwordx4 v[232:233], off
	s_waitcnt vmcnt(8)
	s_waitcnt lgkmcnt(0)
	s_barrier
	v_mfma_f32_16x16x32_bf16 v[62:65], v[138:141], v[190:193], v[62:65]
	v_mfma_f32_16x16x32_bf16 v[58:61], v[146:149], v[190:193], v[58:61]
	v_mfma_f32_16x16x32_bf16 v[46:49], v[138:141], v[204:207], v[46:49]
	v_mfma_f32_16x16x32_bf16 v[42:45], v[146:149], v[204:207], v[42:45]
	v_mfma_f32_16x16x32_bf16 v[30:33], v[138:141], v[214:217], v[30:33]
	v_mfma_f32_16x16x32_bf16 v[26:29], v[146:149], v[214:217], v[26:29]
	v_mfma_f32_16x16x32_bf16 v[14:17], v[138:141], v[222:225], v[14:17]
	v_mfma_f32_16x16x32_bf16 v[10:13], v[146:149], v[222:225], v[10:13]
	v_mfma_f32_16x16x32_bf16 v[62:65], v[142:145], v[194:197], v[62:65]
	v_mfma_f32_16x16x32_bf16 v[58:61], v[150:153], v[194:197], v[58:61]
	v_mfma_f32_16x16x32_bf16 v[46:49], v[142:145], v[208:211], v[46:49]
	v_mfma_f32_16x16x32_bf16 v[42:45], v[150:153], v[208:211], v[42:45]
	v_mfma_f32_16x16x32_bf16 v[30:33], v[142:145], v[218:221], v[30:33]
	v_mfma_f32_16x16x32_bf16 v[26:29], v[150:153], v[218:221], v[26:29]
	v_mfma_f32_16x16x32_bf16 v[14:17], v[142:145], v[226:229], v[14:17]
	v_mfma_f32_16x16x32_bf16 v[10:13], v[150:153], v[226:229], v[10:13]
	s_setprio 0
	s_setprio 1
	v_mfma_f32_16x16x32_bf16 v[54:57], v[154:157], v[190:193], v[54:57]
	v_mfma_f32_16x16x32_bf16 v[50:53], v[182:185], v[190:193], v[50:53]
	v_mfma_f32_16x16x32_bf16 v[38:41], v[154:157], v[204:207], v[38:41]
	v_mfma_f32_16x16x32_bf16 v[34:37], v[182:185], v[204:207], v[34:37]
	v_mfma_f32_16x16x32_bf16 v[22:25], v[154:157], v[214:217], v[22:25]
	v_mfma_f32_16x16x32_bf16 v[18:21], v[182:185], v[214:217], v[18:21]
	v_mfma_f32_16x16x32_bf16 v[6:9], v[154:157], v[222:225], v[6:9]
	v_mfma_f32_16x16x32_bf16 v[2:5], v[182:185], v[222:225], v[2:5]
	v_mfma_f32_16x16x32_bf16 v[54:57], v[170:173], v[194:197], v[54:57]
	v_mfma_f32_16x16x32_bf16 v[50:53], v[186:189], v[194:197], v[50:53]
	v_mfma_f32_16x16x32_bf16 v[38:41], v[170:173], v[208:211], v[38:41]
	v_mfma_f32_16x16x32_bf16 v[34:37], v[186:189], v[208:211], v[34:37]
	v_mfma_f32_16x16x32_bf16 v[22:25], v[170:173], v[218:221], v[22:25]
	v_mfma_f32_16x16x32_bf16 v[18:21], v[186:189], v[218:221], v[18:21]
	v_mfma_f32_16x16x32_bf16 v[6:9], v[170:173], v[226:229], v[6:9]
	v_mfma_f32_16x16x32_bf16 v[2:5], v[186:189], v[226:229], v[2:5]
	s_setprio 0
	s_barrier
	s_add_i32 s76, 0, 0x18000
	v_add_u32_e32 v98, s76, v177
	s_add_i32 s77, 0, 0x1c000
	ds_read_b128 v[138:141], v98
	ds_read_b128 v[142:145], v98 offset:1024
	ds_read_b128 v[146:149], v98 offset:2048
	ds_read_b128 v[150:153], v98 offset:3072
	v_add_u32_e32 v98, s77, v177
	ds_read_b128 v[154:157], v98
	ds_read_b128 v[170:173], v98 offset:1024
	ds_read_b128 v[182:185], v98 offset:2048
	ds_read_b128 v[186:189], v98 offset:3072
	s_add_u32 s62, s62, 0x40000
	s_addc_u32 s63, s63, 0
	s_mov_b32 m0, s12
	v_lshl_add_u64 v[104:105], s[62:63], 0, v[164:165]
	ds_read_b128 v[190:193], v181 offset:32768
	ds_read_b128 v[194:197], v181 offset:33792
	ds_read_b128 v[204:207], v181 offset:34816
	ds_read_b128 v[208:211], v181 offset:35840
	ds_read_b128 v[214:217], v181 offset:36864
	ds_read_b128 v[218:221], v181 offset:37888
	ds_read_b128 v[222:225], v181 offset:38912
	ds_read_b128 v[226:229], v181 offset:39936
	s_setprio 1
	global_load_lds_dwordx4 v[104:105], off
	v_lshl_add_u64 v[104:105], s[62:63], 0, v[160:161]
	s_mov_b32 m0, s13
	s_nop 0
	global_load_lds_dwordx4 v[104:105], off
	s_waitcnt vmcnt(8)
	s_waitcnt lgkmcnt(0)
	s_barrier
	v_mfma_f32_16x16x32_bf16 v[130:133], v[138:141], v[190:193], v[130:133]
	v_mfma_f32_16x16x32_bf16 v[126:129], v[146:149], v[190:193], v[126:129]
	v_mfma_f32_16x16x32_bf16 v[114:117], v[138:141], v[204:207], v[114:117]
	v_mfma_f32_16x16x32_bf16 v[110:113], v[146:149], v[204:207], v[110:113]
	v_mfma_f32_16x16x32_bf16 v[94:97], v[138:141], v[214:217], v[94:97]
	v_mfma_f32_16x16x32_bf16 v[90:93], v[146:149], v[214:217], v[90:93]
	v_mfma_f32_16x16x32_bf16 v[78:81], v[138:141], v[222:225], v[78:81]
	v_mfma_f32_16x16x32_bf16 v[74:77], v[146:149], v[222:225], v[74:77]
	v_mfma_f32_16x16x32_bf16 v[130:133], v[142:145], v[194:197], v[130:133]
	v_mfma_f32_16x16x32_bf16 v[126:129], v[150:153], v[194:197], v[126:129]
	v_mfma_f32_16x16x32_bf16 v[114:117], v[142:145], v[208:211], v[114:117]
	v_mfma_f32_16x16x32_bf16 v[110:113], v[150:153], v[208:211], v[110:113]
	v_mfma_f32_16x16x32_bf16 v[94:97], v[142:145], v[218:221], v[94:97]
	v_mfma_f32_16x16x32_bf16 v[90:93], v[150:153], v[218:221], v[90:93]
	v_mfma_f32_16x16x32_bf16 v[78:81], v[142:145], v[226:229], v[78:81]
	v_mfma_f32_16x16x32_bf16 v[74:77], v[150:153], v[226:229], v[74:77]
	s_setprio 0
	s_setprio 1
	v_mfma_f32_16x16x32_bf16 v[122:125], v[154:157], v[190:193], v[122:125]
	v_mfma_f32_16x16x32_bf16 v[118:121], v[182:185], v[190:193], v[118:121]
	v_mfma_f32_16x16x32_bf16 v[104:107], v[154:157], v[204:207], v[106:109]
	v_mfma_f32_16x16x32_bf16 v[100:103], v[182:185], v[204:207], v[100:103]
	v_mfma_f32_16x16x32_bf16 v[86:89], v[154:157], v[214:217], v[86:89]
	v_mfma_f32_16x16x32_bf16 v[82:85], v[182:185], v[214:217], v[82:85]
	v_mfma_f32_16x16x32_bf16 v[70:73], v[154:157], v[222:225], v[70:73]
	v_mfma_f32_16x16x32_bf16 v[66:69], v[182:185], v[222:225], v[66:69]
	v_mfma_f32_16x16x32_bf16 v[122:125], v[170:173], v[194:197], v[122:125]
	v_mfma_f32_16x16x32_bf16 v[118:121], v[186:189], v[194:197], v[118:121]
	v_mfma_f32_16x16x32_bf16 v[106:109], v[170:173], v[208:211], v[104:107]
	v_mfma_f32_16x16x32_bf16 v[102:105], v[186:189], v[208:211], v[100:103]
	v_mfma_f32_16x16x32_bf16 v[86:89], v[170:173], v[218:221], v[86:89]
	v_mfma_f32_16x16x32_bf16 v[82:85], v[186:189], v[218:221], v[82:85]
	v_mfma_f32_16x16x32_bf16 v[70:73], v[170:173], v[226:229], v[70:73]
	v_mfma_f32_16x16x32_bf16 v[66:69], v[186:189], v[226:229], v[66:69]
	s_setprio 0
	s_barrier
	s_add_i32 s62, s76, s9
	v_lshl_add_u64 v[100:101], v[174:175], 0, s[28:29]
	s_mov_b32 m0, s62
	ds_read_b128 v[190:193], v181 offset:49152
	ds_read_b128 v[194:197], v181 offset:50176
	ds_read_b128 v[204:207], v181 offset:51200
	ds_read_b128 v[208:211], v181 offset:52224
	ds_read_b128 v[214:217], v181 offset:53248
	ds_read_b128 v[218:221], v181 offset:54272
	ds_read_b128 v[222:225], v181 offset:55296
	ds_read_b128 v[226:229], v181 offset:56320
	s_setprio 1
	global_load_lds_dwordx4 v[100:101], off
	s_add_i32 m0, s62, 0x2000
	s_add_u32 s60, s60, 0x40080
	v_lshl_add_u64 v[100:101], v[198:199], 0, s[28:29]
	s_addc_u32 s61, s61, 0
	s_add_i32 s62, s77, s9
	global_load_lds_dwordx4 v[100:101], off
	v_lshl_add_u64 v[100:101], s[60:61], 0, v[162:163]
	s_mov_b32 m0, s62
	s_nop 0
	global_load_lds_dwordx4 v[100:101], off
	v_lshl_add_u64 v[100:101], s[60:61], 0, v[158:159]
	s_add_i32 m0, s62, 0x2000
	s_nop 0
	global_load_lds_dwordx4 v[100:101], off
	v_lshl_add_u64 v[100:101], v[230:231], 0, s[28:29]
	s_mov_b32 m0, s16
	s_nop 0
	global_load_lds_dwordx4 v[100:101], off
	v_lshl_add_u64 v[100:101], v[232:233], 0, s[28:29]
	s_mov_b32 m0, s17
	s_nop 0
	global_load_lds_dwordx4 v[100:101], off
	s_waitcnt vmcnt(8)
	s_waitcnt lgkmcnt(0)
	s_barrier
	v_mfma_f32_16x16x32_bf16 v[62:65], v[138:141], v[190:193], v[62:65]
	v_mfma_f32_16x16x32_bf16 v[58:61], v[146:149], v[190:193], v[58:61]
	v_mfma_f32_16x16x32_bf16 v[46:49], v[138:141], v[204:207], v[46:49]
	v_mfma_f32_16x16x32_bf16 v[42:45], v[146:149], v[204:207], v[42:45]
	v_mfma_f32_16x16x32_bf16 v[30:33], v[138:141], v[214:217], v[30:33]
	v_mfma_f32_16x16x32_bf16 v[26:29], v[146:149], v[214:217], v[26:29]
	v_mfma_f32_16x16x32_bf16 v[14:17], v[138:141], v[222:225], v[14:17]
	v_mfma_f32_16x16x32_bf16 v[10:13], v[146:149], v[222:225], v[10:13]
	v_mfma_f32_16x16x32_bf16 v[62:65], v[142:145], v[194:197], v[62:65]
	v_mfma_f32_16x16x32_bf16 v[58:61], v[150:153], v[194:197], v[58:61]
	v_mfma_f32_16x16x32_bf16 v[46:49], v[142:145], v[208:211], v[46:49]
	v_mfma_f32_16x16x32_bf16 v[42:45], v[150:153], v[208:211], v[42:45]
	v_mfma_f32_16x16x32_bf16 v[30:33], v[142:145], v[218:221], v[30:33]
	v_mfma_f32_16x16x32_bf16 v[26:29], v[150:153], v[218:221], v[26:29]
	v_mfma_f32_16x16x32_bf16 v[14:17], v[142:145], v[226:229], v[14:17]
	v_mfma_f32_16x16x32_bf16 v[10:13], v[150:153], v[226:229], v[10:13]
	s_setprio 0
	s_setprio 1
	v_mfma_f32_16x16x32_bf16 v[54:57], v[154:157], v[190:193], v[54:57]
	v_mfma_f32_16x16x32_bf16 v[50:53], v[182:185], v[190:193], v[50:53]
	v_mfma_f32_16x16x32_bf16 v[38:41], v[154:157], v[204:207], v[38:41]
	v_mfma_f32_16x16x32_bf16 v[34:37], v[182:185], v[204:207], v[34:37]
	v_mfma_f32_16x16x32_bf16 v[22:25], v[154:157], v[214:217], v[22:25]
	v_mfma_f32_16x16x32_bf16 v[18:21], v[182:185], v[214:217], v[18:21]
	v_mfma_f32_16x16x32_bf16 v[6:9], v[154:157], v[222:225], v[6:9]
	v_mfma_f32_16x16x32_bf16 v[2:5], v[182:185], v[222:225], v[2:5]
	v_mfma_f32_16x16x32_bf16 v[54:57], v[170:173], v[194:197], v[54:57]
	v_mfma_f32_16x16x32_bf16 v[50:53], v[186:189], v[194:197], v[50:53]
	v_mfma_f32_16x16x32_bf16 v[38:41], v[170:173], v[208:211], v[38:41]
	v_mfma_f32_16x16x32_bf16 v[34:37], v[186:189], v[208:211], v[34:37]
	v_mfma_f32_16x16x32_bf16 v[22:25], v[170:173], v[218:221], v[22:25]
	v_mfma_f32_16x16x32_bf16 v[18:21], v[186:189], v[218:221], v[18:21]
	v_mfma_f32_16x16x32_bf16 v[6:9], v[170:173], v[226:229], v[6:9]
	v_mfma_f32_16x16x32_bf16 v[2:5], v[186:189], v[226:229], v[2:5]
	s_setprio 0
	s_barrier
	s_add_u32 s58, s58, 0x100
	s_addc_u32 s59, s59, 0
	s_cmp_ge_u32 s75, s57
	s_cbranch_scc1 .LBB0_1113

.LBB0_1328:
	s_add_u32 s44, s42, 0xfffc0080
	s_addc_u32 s45, s43, -1
	s_add_i32 s53, 0, 0x10000
	s_cmp_eq_u32 s52, 12
	s_cselect_b32 s47, s1, s45
	s_cselect_b32 s46, s41, s44
	s_cselect_b32 s45, s48, s51
	s_cselect_b32 s44, s49, s50
	s_add_i32 s56, 0, 0x14000
	v_add_u32_e32 v94, s53, v186
	v_add_u32_e32 v174, s56, v186
	ds_read_b128 v[82:85], v94
	ds_read_b128 v[86:89], v94 offset:1024
	ds_read_b128 v[90:93], v94 offset:2048
	ds_read_b128 v[94:97], v94 offset:3072
	ds_read_b128 v[162:165], v174
	ds_read_b128 v[166:169], v174 offset:1024
	ds_read_b128 v[170:173], v174 offset:2048
	ds_read_b128 v[174:177], v174 offset:3072
	s_add_u32 s100, s42, 0xfffc0000
	s_addc_u32 s101, s43, -1
	v_lshl_add_u64 v[198:199], s[100:101], 0, v[148:149]
	s_mov_b32 m0, s33
	s_nop 0
	s_setprio 1
	global_load_lds_dwordx4 v[198:199], off
	v_lshl_add_u64 v[198:199], s[100:101], 0, v[150:151]
	s_mov_b32 m0, s14
	s_nop 0
	global_load_lds_dwordx4 v[198:199], off
	v_lshl_add_u64 v[198:199], s[42:43], 0, v[158:159]
	s_add_i32 m0, s2, 0xc000
	ds_read_b128 v[178:181], v187
	ds_read_b128 v[182:185], v187 offset:1024
	ds_read_b128 v[190:193], v187 offset:2048
	ds_read_b128 v[194:197], v187 offset:3072
	ds_read_b128 v[204:207], v187 offset:4096
	ds_read_b128 v[208:211], v187 offset:5120
	ds_read_b128 v[214:217], v187 offset:6144
	ds_read_b128 v[218:221], v187 offset:7168
	global_load_lds_dwordx4 v[198:199], off
	v_lshl_add_u64 v[198:199], s[42:43], 0, v[160:161]
	s_add_i32 m0, s2, 0xe000
	s_nop 0
	global_load_lds_dwordx4 v[198:199], off
	s_waitcnt vmcnt(8)
	s_waitcnt lgkmcnt(0)
	s_barrier
	v_mfma_f32_16x16x32_bf16 v[144:147], v[82:85], v[178:181], v[144:147]
	v_mfma_f32_16x16x32_bf16 v[140:143], v[90:93], v[178:181], v[140:143]
	v_mfma_f32_16x16x32_bf16 v[128:131], v[82:85], v[190:193], v[128:131]
	v_mfma_f32_16x16x32_bf16 v[124:127], v[90:93], v[190:193], v[124:127]
	v_mfma_f32_16x16x32_bf16 v[112:115], v[82:85], v[204:207], v[112:115]
	v_mfma_f32_16x16x32_bf16 v[108:111], v[90:93], v[204:207], v[108:111]
	v_mfma_f32_16x16x32_bf16 v[78:81], v[82:85], v[214:217], v[78:81]
	v_mfma_f32_16x16x32_bf16 v[74:77], v[90:93], v[214:217], v[74:77]
	v_mfma_f32_16x16x32_bf16 v[144:147], v[86:89], v[182:185], v[144:147]
	v_mfma_f32_16x16x32_bf16 v[140:143], v[94:97], v[182:185], v[140:143]
	v_mfma_f32_16x16x32_bf16 v[128:131], v[86:89], v[194:197], v[128:131]
	v_mfma_f32_16x16x32_bf16 v[124:127], v[94:97], v[194:197], v[124:127]
	v_mfma_f32_16x16x32_bf16 v[112:115], v[86:89], v[208:211], v[112:115]
	v_mfma_f32_16x16x32_bf16 v[108:111], v[94:97], v[208:211], v[108:111]
	v_mfma_f32_16x16x32_bf16 v[78:81], v[86:89], v[218:221], v[78:81]
	v_mfma_f32_16x16x32_bf16 v[74:77], v[94:97], v[218:221], v[74:77]
	s_setprio 0
	s_setprio 1
	v_mfma_f32_16x16x32_bf16 v[136:139], v[162:165], v[178:181], v[136:139]
	v_mfma_f32_16x16x32_bf16 v[132:135], v[170:173], v[178:181], v[132:135]
	v_mfma_f32_16x16x32_bf16 v[120:123], v[162:165], v[190:193], v[120:123]
	v_mfma_f32_16x16x32_bf16 v[116:119], v[170:173], v[190:193], v[116:119]
	v_mfma_f32_16x16x32_bf16 v[104:107], v[162:165], v[204:207], v[104:107]
	v_mfma_f32_16x16x32_bf16 v[100:103], v[170:173], v[204:207], v[100:103]
	v_mfma_f32_16x16x32_bf16 v[70:73], v[162:165], v[214:217], v[70:73]
	v_mfma_f32_16x16x32_bf16 v[66:69], v[170:173], v[214:217], v[66:69]
	v_mfma_f32_16x16x32_bf16 v[136:139], v[166:169], v[182:185], v[136:139]
	v_mfma_f32_16x16x32_bf16 v[132:135], v[174:177], v[182:185], v[132:135]
	v_mfma_f32_16x16x32_bf16 v[120:123], v[166:169], v[194:197], v[120:123]
	v_mfma_f32_16x16x32_bf16 v[116:119], v[174:177], v[194:197], v[116:119]
	v_mfma_f32_16x16x32_bf16 v[104:107], v[166:169], v[208:211], v[104:107]
	v_mfma_f32_16x16x32_bf16 v[100:103], v[174:177], v[208:211], v[100:103]
	v_mfma_f32_16x16x32_bf16 v[70:73], v[166:169], v[218:221], v[70:73]
	v_mfma_f32_16x16x32_bf16 v[66:69], v[174:177], v[218:221], v[66:69]
	s_setprio 0
	s_barrier
	s_add_i32 s53, s53, s9
	v_lshl_add_u64 v[198:199], s[44:45], 0, v[98:99]
	s_mov_b32 m0, s53
	ds_read_b128 v[178:181], v187 offset:16384
	ds_read_b128 v[182:185], v187 offset:17408
	ds_read_b128 v[190:193], v187 offset:18432
	ds_read_b128 v[194:197], v187 offset:19456
	ds_read_b128 v[204:207], v187 offset:20480
	ds_read_b128 v[208:211], v187 offset:21504
	ds_read_b128 v[214:217], v187 offset:22528
	ds_read_b128 v[218:221], v187 offset:23552
	s_setprio 1
	global_load_lds_dwordx4 v[198:199], off
	s_add_i32 m0, s53, 0x2000
	s_add_u32 s54, s44, 0x40000
	v_lshl_add_u64 v[222:223], s[44:45], 0, v[152:153]
	s_addc_u32 s55, s45, 0
	s_add_i32 s53, s56, s9
	global_load_lds_dwordx4 v[222:223], off
	v_lshl_add_u64 v[224:225], s[54:55], 0, v[98:99]
	s_mov_b32 m0, s53
	s_nop 0
	global_load_lds_dwordx4 v[224:225], off
	v_lshl_add_u64 v[224:225], s[54:55], 0, v[152:153]
	s_add_i32 m0, s53, 0x2000
	s_nop 0
	global_load_lds_dwordx4 v[224:225], off
	s_waitcnt vmcnt(6)
	s_waitcnt lgkmcnt(0)
	s_barrier
	v_mfma_f32_16x16x32_bf16 v[62:65], v[82:85], v[178:181], v[62:65]
	v_mfma_f32_16x16x32_bf16 v[58:61], v[90:93], v[178:181], v[58:61]
	v_mfma_f32_16x16x32_bf16 v[46:49], v[82:85], v[190:193], v[46:49]
	v_mfma_f32_16x16x32_bf16 v[42:45], v[90:93], v[190:193], v[42:45]
	v_mfma_f32_16x16x32_bf16 v[30:33], v[82:85], v[204:207], v[30:33]
	v_mfma_f32_16x16x32_bf16 v[26:29], v[90:93], v[204:207], v[26:29]
	v_mfma_f32_16x16x32_bf16 v[14:17], v[82:85], v[214:217], v[14:17]
	v_mfma_f32_16x16x32_bf16 v[10:13], v[90:93], v[214:217], v[10:13]
	v_mfma_f32_16x16x32_bf16 v[62:65], v[86:89], v[182:185], v[62:65]
	v_mfma_f32_16x16x32_bf16 v[58:61], v[94:97], v[182:185], v[58:61]
	v_mfma_f32_16x16x32_bf16 v[46:49], v[86:89], v[194:197], v[46:49]
	v_mfma_f32_16x16x32_bf16 v[42:45], v[94:97], v[194:197], v[42:45]
	v_mfma_f32_16x16x32_bf16 v[30:33], v[86:89], v[208:211], v[30:33]
	v_mfma_f32_16x16x32_bf16 v[26:29], v[94:97], v[208:211], v[26:29]
	v_mfma_f32_16x16x32_bf16 v[14:17], v[86:89], v[218:221], v[14:17]
	v_mfma_f32_16x16x32_bf16 v[10:13], v[94:97], v[218:221], v[10:13]
	s_setprio 0
	s_setprio 1
	v_mfma_f32_16x16x32_bf16 v[54:57], v[162:165], v[178:181], v[54:57]
	v_mfma_f32_16x16x32_bf16 v[50:53], v[170:173], v[178:181], v[50:53]
	v_mfma_f32_16x16x32_bf16 v[38:41], v[162:165], v[190:193], v[38:41]
	v_mfma_f32_16x16x32_bf16 v[34:37], v[170:173], v[190:193], v[34:37]
	v_mfma_f32_16x16x32_bf16 v[22:25], v[162:165], v[204:207], v[22:25]
	v_mfma_f32_16x16x32_bf16 v[18:21], v[170:173], v[204:207], v[18:21]
	v_mfma_f32_16x16x32_bf16 v[6:9], v[162:165], v[214:217], v[6:9]
	v_mfma_f32_16x16x32_bf16 v[2:5], v[170:173], v[214:217], v[2:5]
	v_mfma_f32_16x16x32_bf16 v[54:57], v[166:169], v[182:185], v[54:57]
	v_mfma_f32_16x16x32_bf16 v[50:53], v[174:177], v[182:185], v[50:53]
	v_mfma_f32_16x16x32_bf16 v[38:41], v[166:169], v[194:197], v[38:41]
	v_mfma_f32_16x16x32_bf16 v[34:37], v[174:177], v[194:197], v[34:37]
	v_mfma_f32_16x16x32_bf16 v[22:25], v[166:169], v[208:211], v[22:25]
	v_mfma_f32_16x16x32_bf16 v[18:21], v[174:177], v[208:211], v[18:21]
	v_mfma_f32_16x16x32_bf16 v[6:9], v[166:169], v[218:221], v[6:9]
	v_mfma_f32_16x16x32_bf16 v[2:5], v[174:177], v[218:221], v[2:5]
	s_setprio 0
	s_barrier
	s_add_i32 s53, 0, 0x18000
	s_add_i32 s54, 0, 0x1c000
	v_add_u32_e32 v94, s53, v186
	v_add_u32_e32 v174, s54, v186
	ds_read_b128 v[82:85], v94
	ds_read_b128 v[86:89], v94 offset:1024
	ds_read_b128 v[90:93], v94 offset:2048
	ds_read_b128 v[94:97], v94 offset:3072
	ds_read_b128 v[162:165], v174
	ds_read_b128 v[166:169], v174 offset:1024
	ds_read_b128 v[170:173], v174 offset:2048
	ds_read_b128 v[174:177], v174 offset:3072
	v_lshl_add_u64 v[224:225], s[46:47], 0, v[148:149]
	s_mov_b32 m0, s2
	v_lshl_add_u64 v[226:227], s[46:47], 0, v[150:151]
	s_setprio 1
	global_load_lds_dwordx4 v[224:225], off
	s_mov_b32 m0, s4
	s_nop 0
	global_load_lds_dwordx4 v[226:227], off
	s_add_u32 s46, s46, 0x40000
	s_addc_u32 s47, s47, 0
	s_mov_b32 m0, s12
	v_lshl_add_u64 v[228:229], s[46:47], 0, v[148:149]
	ds_read_b128 v[178:181], v187 offset:32768
	ds_read_b128 v[182:185], v187 offset:33792
	ds_read_b128 v[190:193], v187 offset:34816
	ds_read_b128 v[194:197], v187 offset:35840
	ds_read_b128 v[204:207], v187 offset:36864
	ds_read_b128 v[208:211], v187 offset:37888
	ds_read_b128 v[214:217], v187 offset:38912
	ds_read_b128 v[218:221], v187 offset:39936
	global_load_lds_dwordx4 v[228:229], off
	v_lshl_add_u64 v[228:229], s[46:47], 0, v[150:151]
	s_mov_b32 m0, s13
	s_nop 0
	global_load_lds_dwordx4 v[228:229], off
	s_waitcnt vmcnt(8)
	s_waitcnt lgkmcnt(0)
	s_barrier
	v_mfma_f32_16x16x32_bf16 v[144:147], v[82:85], v[178:181], v[144:147]
	v_mfma_f32_16x16x32_bf16 v[140:143], v[90:93], v[178:181], v[140:143]
	v_mfma_f32_16x16x32_bf16 v[128:131], v[82:85], v[190:193], v[128:131]
	v_mfma_f32_16x16x32_bf16 v[124:127], v[90:93], v[190:193], v[124:127]
	v_mfma_f32_16x16x32_bf16 v[112:115], v[82:85], v[204:207], v[112:115]
	v_mfma_f32_16x16x32_bf16 v[108:111], v[90:93], v[204:207], v[108:111]
	v_mfma_f32_16x16x32_bf16 v[78:81], v[82:85], v[214:217], v[78:81]
	v_mfma_f32_16x16x32_bf16 v[74:77], v[90:93], v[214:217], v[74:77]
	v_mfma_f32_16x16x32_bf16 v[144:147], v[86:89], v[182:185], v[144:147]
	v_mfma_f32_16x16x32_bf16 v[140:143], v[94:97], v[182:185], v[140:143]
	v_mfma_f32_16x16x32_bf16 v[128:131], v[86:89], v[194:197], v[128:131]
	v_mfma_f32_16x16x32_bf16 v[124:127], v[94:97], v[194:197], v[124:127]
	v_mfma_f32_16x16x32_bf16 v[112:115], v[86:89], v[208:211], v[112:115]
	v_mfma_f32_16x16x32_bf16 v[108:111], v[94:97], v[208:211], v[108:111]
	v_mfma_f32_16x16x32_bf16 v[78:81], v[86:89], v[218:221], v[78:81]
	v_mfma_f32_16x16x32_bf16 v[74:77], v[94:97], v[218:221], v[74:77]
	s_setprio 0
	s_setprio 1
	v_mfma_f32_16x16x32_bf16 v[136:139], v[162:165], v[178:181], v[136:139]
	v_mfma_f32_16x16x32_bf16 v[132:135], v[170:173], v[178:181], v[132:135]
	v_mfma_f32_16x16x32_bf16 v[120:123], v[162:165], v[190:193], v[120:123]
	v_mfma_f32_16x16x32_bf16 v[116:119], v[170:173], v[190:193], v[116:119]
	v_mfma_f32_16x16x32_bf16 v[104:107], v[162:165], v[204:207], v[104:107]
	v_mfma_f32_16x16x32_bf16 v[100:103], v[170:173], v[204:207], v[100:103]
	v_mfma_f32_16x16x32_bf16 v[70:73], v[162:165], v[214:217], v[70:73]
	v_mfma_f32_16x16x32_bf16 v[66:69], v[170:173], v[214:217], v[66:69]
	v_mfma_f32_16x16x32_bf16 v[136:139], v[166:169], v[182:185], v[136:139]
	v_mfma_f32_16x16x32_bf16 v[132:135], v[174:177], v[182:185], v[132:135]
	v_mfma_f32_16x16x32_bf16 v[120:123], v[166:169], v[194:197], v[120:123]
	v_mfma_f32_16x16x32_bf16 v[116:119], v[174:177], v[194:197], v[116:119]
	v_mfma_f32_16x16x32_bf16 v[104:107], v[166:169], v[208:211], v[104:107]
	v_mfma_f32_16x16x32_bf16 v[100:103], v[174:177], v[208:211], v[100:103]
	v_mfma_f32_16x16x32_bf16 v[70:73], v[166:169], v[218:221], v[70:73]
	v_mfma_f32_16x16x32_bf16 v[66:69], v[174:177], v[218:221], v[66:69]
	s_setprio 0
	s_barrier
	s_add_i32 s46, s53, s9
	v_lshl_add_u64 v[198:199], v[198:199], 0, s[28:29]
	s_mov_b32 m0, s46
	ds_read_b128 v[178:181], v187 offset:49152
	ds_read_b128 v[182:185], v187 offset:50176
	ds_read_b128 v[190:193], v187 offset:51200
	ds_read_b128 v[194:197], v187 offset:52224
	ds_read_b128 v[204:207], v187 offset:53248
	ds_read_b128 v[208:211], v187 offset:54272
	ds_read_b128 v[214:217], v187 offset:55296
	ds_read_b128 v[218:221], v187 offset:56320
	s_setprio 1
	global_load_lds_dwordx4 v[198:199], off
	s_add_i32 m0, s46, 0x2000
	s_add_u32 s44, s44, 0x40080
	v_lshl_add_u64 v[198:199], v[222:223], 0, s[28:29]
	s_addc_u32 s45, s45, 0
	s_add_i32 s46, s54, s9
	global_load_lds_dwordx4 v[198:199], off
	v_lshl_add_u64 v[198:199], s[44:45], 0, v[98:99]
	s_mov_b32 m0, s46
	s_nop 0
	global_load_lds_dwordx4 v[198:199], off
	v_lshl_add_u64 v[198:199], s[44:45], 0, v[152:153]
	s_add_i32 m0, s46, 0x2000
	s_nop 0
	global_load_lds_dwordx4 v[198:199], off
	s_waitcnt vmcnt(6)
	s_waitcnt lgkmcnt(0)
	s_barrier
	v_mfma_f32_16x16x32_bf16 v[62:65], v[82:85], v[178:181], v[62:65]
	v_mfma_f32_16x16x32_bf16 v[58:61], v[90:93], v[178:181], v[58:61]
	v_mfma_f32_16x16x32_bf16 v[46:49], v[82:85], v[190:193], v[46:49]
	v_mfma_f32_16x16x32_bf16 v[42:45], v[90:93], v[190:193], v[42:45]
	v_mfma_f32_16x16x32_bf16 v[30:33], v[82:85], v[204:207], v[30:33]
	v_mfma_f32_16x16x32_bf16 v[26:29], v[90:93], v[204:207], v[26:29]
	v_mfma_f32_16x16x32_bf16 v[14:17], v[82:85], v[214:217], v[14:17]
	v_mfma_f32_16x16x32_bf16 v[10:13], v[90:93], v[214:217], v[10:13]
	v_mfma_f32_16x16x32_bf16 v[62:65], v[86:89], v[182:185], v[62:65]
	v_mfma_f32_16x16x32_bf16 v[58:61], v[94:97], v[182:185], v[58:61]
	v_mfma_f32_16x16x32_bf16 v[46:49], v[86:89], v[194:197], v[46:49]
	v_mfma_f32_16x16x32_bf16 v[42:45], v[94:97], v[194:197], v[42:45]
	v_mfma_f32_16x16x32_bf16 v[30:33], v[86:89], v[208:211], v[30:33]
	v_mfma_f32_16x16x32_bf16 v[26:29], v[94:97], v[208:211], v[26:29]
	v_mfma_f32_16x16x32_bf16 v[14:17], v[86:89], v[218:221], v[14:17]
	v_mfma_f32_16x16x32_bf16 v[10:13], v[94:97], v[218:221], v[10:13]
	s_setprio 0
	s_setprio 1
	v_mfma_f32_16x16x32_bf16 v[54:57], v[162:165], v[178:181], v[54:57]
	v_mfma_f32_16x16x32_bf16 v[50:53], v[170:173], v[178:181], v[50:53]
	v_mfma_f32_16x16x32_bf16 v[38:41], v[162:165], v[190:193], v[38:41]
	v_mfma_f32_16x16x32_bf16 v[34:37], v[170:173], v[190:193], v[34:37]
	v_mfma_f32_16x16x32_bf16 v[22:25], v[162:165], v[204:207], v[22:25]
	v_mfma_f32_16x16x32_bf16 v[18:21], v[170:173], v[204:207], v[18:21]
	v_mfma_f32_16x16x32_bf16 v[6:9], v[162:165], v[214:217], v[6:9]
	v_mfma_f32_16x16x32_bf16 v[2:5], v[170:173], v[214:217], v[2:5]
	v_mfma_f32_16x16x32_bf16 v[54:57], v[166:169], v[182:185], v[54:57]
	v_mfma_f32_16x16x32_bf16 v[50:53], v[174:177], v[182:185], v[50:53]
	v_mfma_f32_16x16x32_bf16 v[38:41], v[166:169], v[194:197], v[38:41]
	v_mfma_f32_16x16x32_bf16 v[34:37], v[174:177], v[194:197], v[34:37]
	v_mfma_f32_16x16x32_bf16 v[22:25], v[166:169], v[208:211], v[22:25]
	v_mfma_f32_16x16x32_bf16 v[18:21], v[174:177], v[208:211], v[18:21]
	v_mfma_f32_16x16x32_bf16 v[6:9], v[166:169], v[218:221], v[6:9]
	v_mfma_f32_16x16x32_bf16 v[2:5], v[174:177], v[218:221], v[2:5]
	s_setprio 0
	s_barrier
	s_add_i32 s52, s52, 2
	s_add_u32 s42, s42, 0x100
	s_addc_u32 s43, s43, 0
	s_add_u32 s50, s50, 0x100
	s_addc_u32 s51, s51, 0
	s_cmp_gt_u32 s52, 13
	s_cbranch_scc0 .LBB0_1328
	s_and_b64 vcc, exec, s[76:77]
	s_cbranch_vccz .LBB0_1331
	s_barrier

.LBB0_1529:
	s_add_u32 s50, s48, 0x100
	s_addc_u32 s51, s49, 0
	s_add_i32 s58, 0, 0x10000
	s_cmp_eq_u32 s57, 40
	s_cselect_b32 s55, s1, s51
	s_cselect_b32 s54, s0, s50
	s_cselect_b32 s53, s47, s56
	s_cselect_b32 s52, s46, s33
	s_add_i32 s59, 0, 0x14000
	v_add_u32_e32 v144, s58, v186
	v_add_u32_e32 v160, s59, v186
	ds_read_b128 v[132:135], v144
	ds_read_b128 v[136:139], v144 offset:1024
	ds_read_b128 v[140:143], v144 offset:2048
	ds_read_b128 v[144:147], v144 offset:3072
	ds_read_b128 v[148:151], v160
	ds_read_b128 v[152:155], v160 offset:1024
	ds_read_b128 v[156:159], v160 offset:2048
	ds_read_b128 v[160:163], v160 offset:3072
	v_lshl_add_u64 v[214:215], s[48:49], 0, v[174:175]
	s_add_i32 m0, s4, 0xc000
	ds_read_b128 v[164:167], v187
	ds_read_b128 v[178:181], v187 offset:1024
	ds_read_b128 v[182:185], v187 offset:2048
	ds_read_b128 v[188:191], v187 offset:3072
	ds_read_b128 v[192:195], v187 offset:4096
	ds_read_b128 v[196:199], v187 offset:5120
	ds_read_b128 v[204:207], v187 offset:6144
	ds_read_b128 v[208:211], v187 offset:7168
	s_setprio 1
	global_load_lds_dwordx4 v[214:215], off
	v_lshl_add_u64 v[214:215], s[48:49], 0, v[176:177]
	s_add_i32 m0, s4, 0xe000
	s_nop 0
	global_load_lds_dwordx4 v[214:215], off
	s_waitcnt vmcnt(8)
	s_waitcnt lgkmcnt(0)
	s_barrier
	v_mfma_f32_16x16x32_bf16 v[128:131], v[132:135], v[164:167], v[128:131]
	v_mfma_f32_16x16x32_bf16 v[124:127], v[140:143], v[164:167], v[124:127]
	v_mfma_f32_16x16x32_bf16 v[120:123], v[132:135], v[182:185], v[120:123]
	v_mfma_f32_16x16x32_bf16 v[116:119], v[140:143], v[182:185], v[116:119]
	v_mfma_f32_16x16x32_bf16 v[112:115], v[132:135], v[192:195], v[112:115]
	v_mfma_f32_16x16x32_bf16 v[108:111], v[140:143], v[192:195], v[108:111]
	v_mfma_f32_16x16x32_bf16 v[104:107], v[132:135], v[204:207], v[104:107]
	v_mfma_f32_16x16x32_bf16 v[100:103], v[140:143], v[204:207], v[100:103]
	v_mfma_f32_16x16x32_bf16 v[128:131], v[136:139], v[178:181], v[128:131]
	v_mfma_f32_16x16x32_bf16 v[124:127], v[144:147], v[178:181], v[124:127]
	v_mfma_f32_16x16x32_bf16 v[120:123], v[136:139], v[188:191], v[120:123]
	v_mfma_f32_16x16x32_bf16 v[116:119], v[144:147], v[188:191], v[116:119]
	v_mfma_f32_16x16x32_bf16 v[112:115], v[136:139], v[196:199], v[112:115]
	v_mfma_f32_16x16x32_bf16 v[108:111], v[144:147], v[196:199], v[108:111]
	v_mfma_f32_16x16x32_bf16 v[104:107], v[136:139], v[208:211], v[104:107]
	v_mfma_f32_16x16x32_bf16 v[100:103], v[144:147], v[208:211], v[100:103]
	s_setprio 0
	s_setprio 1
	v_mfma_f32_16x16x32_bf16 v[62:65], v[148:151], v[164:167], v[62:65]
	v_mfma_f32_16x16x32_bf16 v[58:61], v[156:159], v[164:167], v[58:61]
	v_mfma_f32_16x16x32_bf16 v[54:57], v[148:151], v[182:185], v[54:57]
	v_mfma_f32_16x16x32_bf16 v[50:53], v[156:159], v[182:185], v[50:53]
	v_mfma_f32_16x16x32_bf16 v[46:49], v[148:151], v[192:195], v[46:49]
	v_mfma_f32_16x16x32_bf16 v[42:45], v[156:159], v[192:195], v[42:45]
	v_mfma_f32_16x16x32_bf16 v[38:41], v[148:151], v[204:207], v[38:41]
	v_mfma_f32_16x16x32_bf16 v[34:37], v[156:159], v[204:207], v[34:37]
	v_mfma_f32_16x16x32_bf16 v[62:65], v[152:155], v[178:181], v[62:65]
	v_mfma_f32_16x16x32_bf16 v[58:61], v[160:163], v[178:181], v[58:61]
	v_mfma_f32_16x16x32_bf16 v[54:57], v[152:155], v[188:191], v[54:57]
	v_mfma_f32_16x16x32_bf16 v[50:53], v[160:163], v[188:191], v[50:53]
	v_mfma_f32_16x16x32_bf16 v[46:49], v[152:155], v[196:199], v[46:49]
	v_mfma_f32_16x16x32_bf16 v[42:45], v[160:163], v[196:199], v[42:45]
	v_mfma_f32_16x16x32_bf16 v[38:41], v[152:155], v[208:211], v[38:41]
	v_mfma_f32_16x16x32_bf16 v[34:37], v[160:163], v[208:211], v[34:37]
	s_setprio 0
	s_barrier
	s_add_i32 s48, s58, s2
	v_lshl_add_u64 v[214:215], s[52:53], 0, v[98:99]
	s_mov_b32 m0, s48
	ds_read_b128 v[164:167], v187 offset:16384
	ds_read_b128 v[178:181], v187 offset:17408
	ds_read_b128 v[182:185], v187 offset:18432
	ds_read_b128 v[188:191], v187 offset:19456
	ds_read_b128 v[192:195], v187 offset:20480
	ds_read_b128 v[196:199], v187 offset:21504
	ds_read_b128 v[204:207], v187 offset:22528
	ds_read_b128 v[208:211], v187 offset:23552
	s_setprio 1
	global_load_lds_dwordx4 v[214:215], off
	s_add_i32 m0, s48, 0x2000
	s_add_u32 s48, s52, 0xb0000
	v_lshl_add_u64 v[216:217], s[52:53], 0, v[168:169]
	s_addc_u32 s49, s53, 0
	s_add_i32 s58, s59, s2
	global_load_lds_dwordx4 v[216:217], off
	v_lshl_add_u64 v[218:219], s[48:49], 0, v[98:99]
	s_mov_b32 m0, s58
	v_lshl_add_u64 v[220:221], s[54:55], 0, v[170:171]
	global_load_lds_dwordx4 v[218:219], off
	v_lshl_add_u64 v[218:219], s[48:49], 0, v[168:169]
	s_add_i32 m0, s58, 0x2000
	s_nop 0
	global_load_lds_dwordx4 v[218:219], off
	v_lshl_add_u64 v[218:219], s[54:55], 0, v[172:173]
	s_mov_b32 m0, s4
	s_nop 0
	global_load_lds_dwordx4 v[218:219], off
	s_mov_b32 m0, s7
	s_nop 0
	global_load_lds_dwordx4 v[220:221], off
	s_waitcnt vmcnt(8)
	s_waitcnt lgkmcnt(0)
	s_barrier
	v_mfma_f32_16x16x32_bf16 v[94:97], v[132:135], v[164:167], v[94:97]
	v_mfma_f32_16x16x32_bf16 v[90:93], v[140:143], v[164:167], v[90:93]
	v_mfma_f32_16x16x32_bf16 v[86:89], v[132:135], v[182:185], v[86:89]
	v_mfma_f32_16x16x32_bf16 v[82:85], v[140:143], v[182:185], v[82:85]
	v_mfma_f32_16x16x32_bf16 v[78:81], v[132:135], v[192:195], v[78:81]
	v_mfma_f32_16x16x32_bf16 v[74:77], v[140:143], v[192:195], v[74:77]
	v_mfma_f32_16x16x32_bf16 v[70:73], v[132:135], v[204:207], v[70:73]
	v_mfma_f32_16x16x32_bf16 v[66:69], v[140:143], v[204:207], v[66:69]
	v_mfma_f32_16x16x32_bf16 v[94:97], v[136:139], v[178:181], v[94:97]
	v_mfma_f32_16x16x32_bf16 v[90:93], v[144:147], v[178:181], v[90:93]
	v_mfma_f32_16x16x32_bf16 v[86:89], v[136:139], v[188:191], v[86:89]
	v_mfma_f32_16x16x32_bf16 v[82:85], v[144:147], v[188:191], v[82:85]
	v_mfma_f32_16x16x32_bf16 v[78:81], v[136:139], v[196:199], v[78:81]
	v_mfma_f32_16x16x32_bf16 v[74:77], v[144:147], v[196:199], v[74:77]
	v_mfma_f32_16x16x32_bf16 v[70:73], v[136:139], v[208:211], v[70:73]
	v_mfma_f32_16x16x32_bf16 v[66:69], v[144:147], v[208:211], v[66:69]
	s_setprio 0
	s_setprio 1
	v_mfma_f32_16x16x32_bf16 v[30:33], v[148:151], v[164:167], v[30:33]
	v_mfma_f32_16x16x32_bf16 v[26:29], v[156:159], v[164:167], v[26:29]
	v_mfma_f32_16x16x32_bf16 v[22:25], v[148:151], v[182:185], v[22:25]
	v_mfma_f32_16x16x32_bf16 v[18:21], v[156:159], v[182:185], v[18:21]
	v_mfma_f32_16x16x32_bf16 v[14:17], v[148:151], v[192:195], v[14:17]
	v_mfma_f32_16x16x32_bf16 v[10:13], v[156:159], v[192:195], v[10:13]
	v_mfma_f32_16x16x32_bf16 v[6:9], v[148:151], v[204:207], v[6:9]
	v_mfma_f32_16x16x32_bf16 v[2:5], v[156:159], v[204:207], v[2:5]
	v_mfma_f32_16x16x32_bf16 v[30:33], v[152:155], v[178:181], v[30:33]
	v_mfma_f32_16x16x32_bf16 v[26:29], v[160:163], v[178:181], v[26:29]
	v_mfma_f32_16x16x32_bf16 v[22:25], v[152:155], v[188:191], v[22:25]
	v_mfma_f32_16x16x32_bf16 v[18:21], v[160:163], v[188:191], v[18:21]
	v_mfma_f32_16x16x32_bf16 v[14:17], v[152:155], v[196:199], v[14:17]
	v_mfma_f32_16x16x32_bf16 v[10:13], v[160:163], v[196:199], v[10:13]
	v_mfma_f32_16x16x32_bf16 v[6:9], v[152:155], v[208:211], v[6:9]
	v_mfma_f32_16x16x32_bf16 v[2:5], v[160:163], v[208:211], v[2:5]
	s_setprio 0
	s_barrier
	s_add_i32 s58, 0, 0x18000
	s_add_i32 s59, 0, 0x1c000
	v_add_u32_e32 v144, s58, v186
	v_add_u32_e32 v160, s59, v186
	ds_read_b128 v[132:135], v144
	ds_read_b128 v[136:139], v144 offset:1024
	ds_read_b128 v[140:143], v144 offset:2048
	ds_read_b128 v[144:147], v144 offset:3072
	ds_read_b128 v[148:151], v160
	ds_read_b128 v[152:155], v160 offset:1024
	ds_read_b128 v[156:159], v160 offset:2048
	ds_read_b128 v[160:163], v160 offset:3072
	s_add_u32 s48, s54, 0xb0000
	s_addc_u32 s49, s55, 0
	s_mov_b32 m0, s8
	v_lshl_add_u64 v[222:223], s[48:49], 0, v[172:173]
	ds_read_b128 v[164:167], v187 offset:32768
	ds_read_b128 v[178:181], v187 offset:33792
	ds_read_b128 v[182:185], v187 offset:34816
	ds_read_b128 v[188:191], v187 offset:35840
	ds_read_b128 v[192:195], v187 offset:36864
	ds_read_b128 v[196:199], v187 offset:37888
	ds_read_b128 v[204:207], v187 offset:38912
	ds_read_b128 v[208:211], v187 offset:39936
	s_setprio 1
	global_load_lds_dwordx4 v[222:223], off
	v_lshl_add_u64 v[222:223], s[48:49], 0, v[170:171]
	s_mov_b32 m0, s9
	s_nop 0
	global_load_lds_dwordx4 v[222:223], off
	s_waitcnt vmcnt(8)
	s_waitcnt lgkmcnt(0)
	s_barrier
	v_mfma_f32_16x16x32_bf16 v[128:131], v[132:135], v[164:167], v[128:131]
	v_mfma_f32_16x16x32_bf16 v[124:127], v[140:143], v[164:167], v[124:127]
	v_mfma_f32_16x16x32_bf16 v[120:123], v[132:135], v[182:185], v[120:123]
	v_mfma_f32_16x16x32_bf16 v[116:119], v[140:143], v[182:185], v[116:119]
	v_mfma_f32_16x16x32_bf16 v[112:115], v[132:135], v[192:195], v[112:115]
	v_mfma_f32_16x16x32_bf16 v[108:111], v[140:143], v[192:195], v[108:111]
	v_mfma_f32_16x16x32_bf16 v[104:107], v[132:135], v[204:207], v[104:107]
	v_mfma_f32_16x16x32_bf16 v[100:103], v[140:143], v[204:207], v[100:103]
	v_mfma_f32_16x16x32_bf16 v[128:131], v[136:139], v[178:181], v[128:131]
	v_mfma_f32_16x16x32_bf16 v[124:127], v[144:147], v[178:181], v[124:127]
	v_mfma_f32_16x16x32_bf16 v[120:123], v[136:139], v[188:191], v[120:123]
	v_mfma_f32_16x16x32_bf16 v[116:119], v[144:147], v[188:191], v[116:119]
	v_mfma_f32_16x16x32_bf16 v[112:115], v[136:139], v[196:199], v[112:115]
	v_mfma_f32_16x16x32_bf16 v[108:111], v[144:147], v[196:199], v[108:111]
	v_mfma_f32_16x16x32_bf16 v[104:107], v[136:139], v[208:211], v[104:107]
	v_mfma_f32_16x16x32_bf16 v[100:103], v[144:147], v[208:211], v[100:103]
	s_setprio 0
	s_setprio 1
	v_mfma_f32_16x16x32_bf16 v[62:65], v[148:151], v[164:167], v[62:65]
	v_mfma_f32_16x16x32_bf16 v[58:61], v[156:159], v[164:167], v[58:61]
	v_mfma_f32_16x16x32_bf16 v[54:57], v[148:151], v[182:185], v[54:57]
	v_mfma_f32_16x16x32_bf16 v[50:53], v[156:159], v[182:185], v[50:53]
	v_mfma_f32_16x16x32_bf16 v[46:49], v[148:151], v[192:195], v[46:49]
	v_mfma_f32_16x16x32_bf16 v[42:45], v[156:159], v[192:195], v[42:45]
	v_mfma_f32_16x16x32_bf16 v[38:41], v[148:151], v[204:207], v[38:41]
	v_mfma_f32_16x16x32_bf16 v[34:37], v[156:159], v[204:207], v[34:37]
	v_mfma_f32_16x16x32_bf16 v[62:65], v[152:155], v[178:181], v[62:65]
	v_mfma_f32_16x16x32_bf16 v[58:61], v[160:163], v[178:181], v[58:61]
	v_mfma_f32_16x16x32_bf16 v[54:57], v[152:155], v[188:191], v[54:57]
	v_mfma_f32_16x16x32_bf16 v[50:53], v[160:163], v[188:191], v[50:53]
	v_mfma_f32_16x16x32_bf16 v[46:49], v[152:155], v[196:199], v[46:49]
	v_mfma_f32_16x16x32_bf16 v[42:45], v[160:163], v[196:199], v[42:45]
	v_mfma_f32_16x16x32_bf16 v[38:41], v[152:155], v[208:211], v[38:41]
	v_mfma_f32_16x16x32_bf16 v[34:37], v[160:163], v[208:211], v[34:37]
	s_setprio 0
	s_barrier
	s_add_i32 s48, s58, s2
	v_lshl_add_u64 v[214:215], v[214:215], 0, s[28:29]
	s_mov_b32 m0, s48
	ds_read_b128 v[164:167], v187 offset:49152
	ds_read_b128 v[178:181], v187 offset:50176
	ds_read_b128 v[182:185], v187 offset:51200
	ds_read_b128 v[188:191], v187 offset:52224
	ds_read_b128 v[192:195], v187 offset:53248
	ds_read_b128 v[196:199], v187 offset:54272
	ds_read_b128 v[204:207], v187 offset:55296
	ds_read_b128 v[208:211], v187 offset:56320
	s_setprio 1
	global_load_lds_dwordx4 v[214:215], off
	s_add_i32 m0, s48, 0x2000
	s_add_u32 s48, s52, 0xb0080
	v_lshl_add_u64 v[214:215], v[216:217], 0, s[28:29]
	s_addc_u32 s49, s53, 0
	s_add_i32 s52, s59, s2
	global_load_lds_dwordx4 v[214:215], off
	v_lshl_add_u64 v[214:215], s[48:49], 0, v[98:99]
	s_mov_b32 m0, s52
	s_nop 0
	global_load_lds_dwordx4 v[214:215], off
	v_lshl_add_u64 v[214:215], s[48:49], 0, v[168:169]
	s_add_i32 m0, s52, 0x2000
	s_nop 0
	global_load_lds_dwordx4 v[214:215], off
	v_lshl_add_u64 v[214:215], v[218:219], 0, s[28:29]
	s_mov_b32 m0, s12
	s_nop 0
	global_load_lds_dwordx4 v[214:215], off
	v_lshl_add_u64 v[214:215], v[220:221], 0, s[28:29]
	s_mov_b32 m0, s13
	s_nop 0
	global_load_lds_dwordx4 v[214:215], off
	s_waitcnt vmcnt(8)
	s_waitcnt lgkmcnt(0)
	s_barrier
	v_mfma_f32_16x16x32_bf16 v[94:97], v[132:135], v[164:167], v[94:97]
	v_mfma_f32_16x16x32_bf16 v[90:93], v[140:143], v[164:167], v[90:93]
	v_mfma_f32_16x16x32_bf16 v[86:89], v[132:135], v[182:185], v[86:89]
	v_mfma_f32_16x16x32_bf16 v[82:85], v[140:143], v[182:185], v[82:85]
	v_mfma_f32_16x16x32_bf16 v[78:81], v[132:135], v[192:195], v[78:81]
	v_mfma_f32_16x16x32_bf16 v[74:77], v[140:143], v[192:195], v[74:77]
	v_mfma_f32_16x16x32_bf16 v[70:73], v[132:135], v[204:207], v[70:73]
	v_mfma_f32_16x16x32_bf16 v[66:69], v[140:143], v[204:207], v[66:69]
	v_mfma_f32_16x16x32_bf16 v[94:97], v[136:139], v[178:181], v[94:97]
	v_mfma_f32_16x16x32_bf16 v[90:93], v[144:147], v[178:181], v[90:93]
	v_mfma_f32_16x16x32_bf16 v[86:89], v[136:139], v[188:191], v[86:89]
	v_mfma_f32_16x16x32_bf16 v[82:85], v[144:147], v[188:191], v[82:85]
	v_mfma_f32_16x16x32_bf16 v[78:81], v[136:139], v[196:199], v[78:81]
	v_mfma_f32_16x16x32_bf16 v[74:77], v[144:147], v[196:199], v[74:77]
	v_mfma_f32_16x16x32_bf16 v[70:73], v[136:139], v[208:211], v[70:73]
	v_mfma_f32_16x16x32_bf16 v[66:69], v[144:147], v[208:211], v[66:69]
	s_setprio 0
	s_setprio 1
	v_mfma_f32_16x16x32_bf16 v[30:33], v[148:151], v[164:167], v[30:33]
	v_mfma_f32_16x16x32_bf16 v[26:29], v[156:159], v[164:167], v[26:29]
	v_mfma_f32_16x16x32_bf16 v[22:25], v[148:151], v[182:185], v[22:25]
	v_mfma_f32_16x16x32_bf16 v[18:21], v[156:159], v[182:185], v[18:21]
	v_mfma_f32_16x16x32_bf16 v[14:17], v[148:151], v[192:195], v[14:17]
	v_mfma_f32_16x16x32_bf16 v[10:13], v[156:159], v[192:195], v[10:13]
	v_mfma_f32_16x16x32_bf16 v[6:9], v[148:151], v[204:207], v[6:9]
	v_mfma_f32_16x16x32_bf16 v[2:5], v[156:159], v[204:207], v[2:5]
	v_mfma_f32_16x16x32_bf16 v[30:33], v[152:155], v[178:181], v[30:33]
	v_mfma_f32_16x16x32_bf16 v[26:29], v[160:163], v[178:181], v[26:29]
	v_mfma_f32_16x16x32_bf16 v[22:25], v[152:155], v[188:191], v[22:25]
	v_mfma_f32_16x16x32_bf16 v[18:21], v[160:163], v[188:191], v[18:21]
	v_mfma_f32_16x16x32_bf16 v[14:17], v[152:155], v[196:199], v[14:17]
	v_mfma_f32_16x16x32_bf16 v[10:13], v[160:163], v[196:199], v[10:13]
	v_mfma_f32_16x16x32_bf16 v[6:9], v[152:155], v[208:211], v[6:9]
	v_mfma_f32_16x16x32_bf16 v[2:5], v[160:163], v[208:211], v[2:5]
	s_setprio 0
	s_barrier
	s_add_i32 s57, s57, 2
	s_add_u32 s33, s33, 0x100
	s_addc_u32 s56, s56, 0
	s_cmp_gt_u32 s57, 41
	s_mov_b64 s[48:49], s[50:51]
	s_cbranch_scc0 .LBB0_1529
	s_and_b64 vcc, exec, s[44:45]
	s_cbranch_vccz .LBB0_1532
	s_barrier

.LBB0_1553:
	s_add_i32 s63, s54, 2
	s_add_u32 s52, s50, 0x100
	s_addc_u32 s53, s51, 0
	s_add_i32 s64, 0, 0x10000
	s_cmp_eq_u32 s60, s54
	s_cselect_b32 s57, s45, s53
	s_cselect_b32 s56, s44, s52
	s_cselect_b32 s55, s47, s62
	s_cselect_b32 s54, s46, s61
	s_add_i32 s65, 0, 0x14000
	v_add_u32_e32 v144, s64, v198
	v_add_u32_e32 v160, s65, v198
	s_waitcnt lgkmcnt(0)
	ds_read_b128 v[132:135], v144
	ds_read_b128 v[136:139], v144 offset:1024
	ds_read_b128 v[140:143], v144 offset:2048
	ds_read_b128 v[144:147], v144 offset:3072
	ds_read_b128 v[148:151], v160
	ds_read_b128 v[152:155], v160 offset:1024
	ds_read_b128 v[156:159], v160 offset:2048
	ds_read_b128 v[160:163], v160 offset:3072
	v_lshl_add_u64 v[214:215], s[50:51], 0, v[178:179]
	s_add_i32 m0, s4, 0xc000
	ds_read_b128 v[164:167], v199
	ds_read_b128 v[168:171], v199 offset:1024
	ds_read_b128 v[182:185], v199 offset:2048
	ds_read_b128 v[186:189], v199 offset:3072
	ds_read_b128 v[190:193], v199 offset:4096
	ds_read_b128 v[194:197], v199 offset:5120
	ds_read_b128 v[204:207], v199 offset:6144
	ds_read_b128 v[208:211], v199 offset:7168
	s_setprio 1
	global_load_lds_dwordx4 v[214:215], off
	v_lshl_add_u64 v[214:215], s[50:51], 0, v[180:181]
	s_add_i32 m0, s4, 0xe000
	s_nop 0
	global_load_lds_dwordx4 v[214:215], off
	s_waitcnt vmcnt(8)
	s_waitcnt lgkmcnt(0)
	s_barrier
	v_mfma_f32_16x16x32_bf16 v[128:131], v[132:135], v[164:167], v[128:131]
	v_mfma_f32_16x16x32_bf16 v[124:127], v[140:143], v[164:167], v[124:127]
	v_mfma_f32_16x16x32_bf16 v[120:123], v[132:135], v[182:185], v[120:123]
	v_mfma_f32_16x16x32_bf16 v[116:119], v[140:143], v[182:185], v[116:119]
	v_mfma_f32_16x16x32_bf16 v[104:107], v[132:135], v[190:193], v[104:107]
	v_mfma_f32_16x16x32_bf16 v[100:103], v[140:143], v[190:193], v[100:103]
	v_mfma_f32_16x16x32_bf16 v[86:89], v[132:135], v[204:207], v[86:89]
	v_mfma_f32_16x16x32_bf16 v[82:85], v[140:143], v[204:207], v[82:85]
	v_mfma_f32_16x16x32_bf16 v[128:131], v[136:139], v[168:171], v[128:131]
	v_mfma_f32_16x16x32_bf16 v[124:127], v[144:147], v[168:171], v[124:127]
	v_mfma_f32_16x16x32_bf16 v[120:123], v[136:139], v[186:189], v[120:123]
	v_mfma_f32_16x16x32_bf16 v[116:119], v[144:147], v[186:189], v[116:119]
	v_mfma_f32_16x16x32_bf16 v[104:107], v[136:139], v[194:197], v[104:107]
	v_mfma_f32_16x16x32_bf16 v[100:103], v[144:147], v[194:197], v[100:103]
	v_mfma_f32_16x16x32_bf16 v[86:89], v[136:139], v[208:211], v[86:89]
	v_mfma_f32_16x16x32_bf16 v[82:85], v[144:147], v[208:211], v[82:85]
	s_setprio 0
	s_setprio 1
	v_mfma_f32_16x16x32_bf16 v[112:115], v[148:151], v[164:167], v[112:115]
	v_mfma_f32_16x16x32_bf16 v[108:111], v[156:159], v[164:167], v[108:111]
	v_mfma_f32_16x16x32_bf16 v[94:97], v[148:151], v[182:185], v[94:97]
	v_mfma_f32_16x16x32_bf16 v[90:93], v[156:159], v[182:185], v[90:93]
	v_mfma_f32_16x16x32_bf16 v[78:81], v[148:151], v[190:193], v[78:81]
	v_mfma_f32_16x16x32_bf16 v[74:77], v[156:159], v[190:193], v[74:77]
	v_mfma_f32_16x16x32_bf16 v[70:73], v[148:151], v[204:207], v[70:73]
	v_mfma_f32_16x16x32_bf16 v[66:69], v[156:159], v[204:207], v[66:69]
	v_mfma_f32_16x16x32_bf16 v[112:115], v[152:155], v[168:171], v[112:115]
	v_mfma_f32_16x16x32_bf16 v[108:111], v[160:163], v[168:171], v[108:111]
	v_mfma_f32_16x16x32_bf16 v[94:97], v[152:155], v[186:189], v[94:97]
	v_mfma_f32_16x16x32_bf16 v[90:93], v[160:163], v[186:189], v[90:93]
	v_mfma_f32_16x16x32_bf16 v[78:81], v[152:155], v[194:197], v[78:81]
	v_mfma_f32_16x16x32_bf16 v[74:77], v[160:163], v[194:197], v[74:77]
	v_mfma_f32_16x16x32_bf16 v[70:73], v[152:155], v[208:211], v[70:73]
	v_mfma_f32_16x16x32_bf16 v[66:69], v[160:163], v[208:211], v[66:69]
	s_setprio 0
	s_barrier
	s_add_i32 s50, s64, s2
	v_lshl_add_u64 v[214:215], s[54:55], 0, v[98:99]
	s_mov_b32 m0, s50
	ds_read_b128 v[164:167], v199 offset:16384
	ds_read_b128 v[168:171], v199 offset:17408
	ds_read_b128 v[182:185], v199 offset:18432
	ds_read_b128 v[186:189], v199 offset:19456
	ds_read_b128 v[190:193], v199 offset:20480
	ds_read_b128 v[194:197], v199 offset:21504
	ds_read_b128 v[204:207], v199 offset:22528
	ds_read_b128 v[208:211], v199 offset:23552
	s_setprio 1
	global_load_lds_dwordx4 v[214:215], off
	s_add_i32 m0, s50, 0x2000
	s_add_u32 s50, s54, 0xb0000
	v_lshl_add_u64 v[216:217], s[54:55], 0, v[172:173]
	s_addc_u32 s51, s55, 0
	s_add_i32 s64, s65, s2
	global_load_lds_dwordx4 v[216:217], off
	v_lshl_add_u64 v[218:219], s[50:51], 0, v[98:99]
	s_mov_b32 m0, s64
	v_lshl_add_u64 v[220:221], s[56:57], 0, v[174:175]
	global_load_lds_dwordx4 v[218:219], off
	v_lshl_add_u64 v[218:219], s[50:51], 0, v[172:173]
	s_add_i32 m0, s64, 0x2000
	s_nop 0
	global_load_lds_dwordx4 v[218:219], off
	v_lshl_add_u64 v[218:219], s[56:57], 0, v[176:177]
	s_mov_b32 m0, s4
	s_nop 0
	global_load_lds_dwordx4 v[218:219], off
	s_mov_b32 m0, s7
	s_nop 0
	global_load_lds_dwordx4 v[220:221], off
	s_waitcnt vmcnt(8)
	s_waitcnt lgkmcnt(0)
	s_barrier
	v_mfma_f32_16x16x32_bf16 v[62:65], v[132:135], v[164:167], v[62:65]
	v_mfma_f32_16x16x32_bf16 v[58:61], v[140:143], v[164:167], v[58:61]
	v_mfma_f32_16x16x32_bf16 v[54:57], v[132:135], v[182:185], v[54:57]
	v_mfma_f32_16x16x32_bf16 v[50:53], v[140:143], v[182:185], v[50:53]
	v_mfma_f32_16x16x32_bf16 v[38:41], v[132:135], v[190:193], v[38:41]
	v_mfma_f32_16x16x32_bf16 v[34:37], v[140:143], v[190:193], v[34:37]
	v_mfma_f32_16x16x32_bf16 v[22:25], v[132:135], v[204:207], v[22:25]
	v_mfma_f32_16x16x32_bf16 v[18:21], v[140:143], v[204:207], v[18:21]
	v_mfma_f32_16x16x32_bf16 v[62:65], v[136:139], v[168:171], v[62:65]
	v_mfma_f32_16x16x32_bf16 v[58:61], v[144:147], v[168:171], v[58:61]
	v_mfma_f32_16x16x32_bf16 v[54:57], v[136:139], v[186:189], v[54:57]
	v_mfma_f32_16x16x32_bf16 v[50:53], v[144:147], v[186:189], v[50:53]
	v_mfma_f32_16x16x32_bf16 v[38:41], v[136:139], v[194:197], v[38:41]
	v_mfma_f32_16x16x32_bf16 v[34:37], v[144:147], v[194:197], v[34:37]
	v_mfma_f32_16x16x32_bf16 v[22:25], v[136:139], v[208:211], v[22:25]
	v_mfma_f32_16x16x32_bf16 v[18:21], v[144:147], v[208:211], v[18:21]
	s_setprio 0
	s_setprio 1
	v_mfma_f32_16x16x32_bf16 v[46:49], v[148:151], v[164:167], v[46:49]
	v_mfma_f32_16x16x32_bf16 v[42:45], v[156:159], v[164:167], v[42:45]
	v_mfma_f32_16x16x32_bf16 v[30:33], v[148:151], v[182:185], v[30:33]
	v_mfma_f32_16x16x32_bf16 v[26:29], v[156:159], v[182:185], v[26:29]
	v_mfma_f32_16x16x32_bf16 v[14:17], v[148:151], v[190:193], v[14:17]
	v_mfma_f32_16x16x32_bf16 v[10:13], v[156:159], v[190:193], v[10:13]
	v_mfma_f32_16x16x32_bf16 v[6:9], v[148:151], v[204:207], v[6:9]
	v_mfma_f32_16x16x32_bf16 v[2:5], v[156:159], v[204:207], v[2:5]
	v_mfma_f32_16x16x32_bf16 v[46:49], v[152:155], v[168:171], v[46:49]
	v_mfma_f32_16x16x32_bf16 v[42:45], v[160:163], v[168:171], v[42:45]
	v_mfma_f32_16x16x32_bf16 v[30:33], v[152:155], v[186:189], v[30:33]
	v_mfma_f32_16x16x32_bf16 v[26:29], v[160:163], v[186:189], v[26:29]
	v_mfma_f32_16x16x32_bf16 v[14:17], v[152:155], v[194:197], v[14:17]
	v_mfma_f32_16x16x32_bf16 v[10:13], v[160:163], v[194:197], v[10:13]
	v_mfma_f32_16x16x32_bf16 v[6:9], v[152:155], v[208:211], v[6:9]
	v_mfma_f32_16x16x32_bf16 v[2:5], v[160:163], v[208:211], v[2:5]
	s_setprio 0
	s_barrier
	s_add_i32 s64, 0, 0x18000
	s_add_i32 s65, 0, 0x1c000
	v_add_u32_e32 v144, s64, v198
	v_add_u32_e32 v160, s65, v198
	ds_read_b128 v[132:135], v144
	ds_read_b128 v[136:139], v144 offset:1024
	ds_read_b128 v[140:143], v144 offset:2048
	ds_read_b128 v[144:147], v144 offset:3072
	ds_read_b128 v[148:151], v160
	ds_read_b128 v[152:155], v160 offset:1024
	ds_read_b128 v[156:159], v160 offset:2048
	ds_read_b128 v[160:163], v160 offset:3072
	s_add_u32 s50, s56, 0xb0000
	s_addc_u32 s51, s57, 0
	s_mov_b32 m0, s8
	v_lshl_add_u64 v[222:223], s[50:51], 0, v[176:177]
	ds_read_b128 v[164:167], v199 offset:32768
	ds_read_b128 v[168:171], v199 offset:33792
	ds_read_b128 v[182:185], v199 offset:34816
	ds_read_b128 v[186:189], v199 offset:35840
	ds_read_b128 v[190:193], v199 offset:36864
	ds_read_b128 v[194:197], v199 offset:37888
	ds_read_b128 v[204:207], v199 offset:38912
	ds_read_b128 v[208:211], v199 offset:39936
	s_setprio 1
	global_load_lds_dwordx4 v[222:223], off
	v_lshl_add_u64 v[222:223], s[50:51], 0, v[174:175]
	s_mov_b32 m0, s9
	s_nop 0
	global_load_lds_dwordx4 v[222:223], off
	s_waitcnt vmcnt(8)
	s_waitcnt lgkmcnt(0)
	s_barrier
	v_mfma_f32_16x16x32_bf16 v[128:131], v[132:135], v[164:167], v[128:131]
	v_mfma_f32_16x16x32_bf16 v[124:127], v[140:143], v[164:167], v[124:127]
	v_mfma_f32_16x16x32_bf16 v[120:123], v[132:135], v[182:185], v[120:123]
	v_mfma_f32_16x16x32_bf16 v[116:119], v[140:143], v[182:185], v[116:119]
	v_mfma_f32_16x16x32_bf16 v[104:107], v[132:135], v[190:193], v[104:107]
	v_mfma_f32_16x16x32_bf16 v[100:103], v[140:143], v[190:193], v[100:103]
	v_mfma_f32_16x16x32_bf16 v[86:89], v[132:135], v[204:207], v[86:89]
	v_mfma_f32_16x16x32_bf16 v[82:85], v[140:143], v[204:207], v[82:85]
	v_mfma_f32_16x16x32_bf16 v[128:131], v[136:139], v[168:171], v[128:131]
	v_mfma_f32_16x16x32_bf16 v[124:127], v[144:147], v[168:171], v[124:127]
	v_mfma_f32_16x16x32_bf16 v[120:123], v[136:139], v[186:189], v[120:123]
	v_mfma_f32_16x16x32_bf16 v[116:119], v[144:147], v[186:189], v[116:119]
	v_mfma_f32_16x16x32_bf16 v[104:107], v[136:139], v[194:197], v[104:107]
	v_mfma_f32_16x16x32_bf16 v[100:103], v[144:147], v[194:197], v[100:103]
	v_mfma_f32_16x16x32_bf16 v[86:89], v[136:139], v[208:211], v[86:89]
	v_mfma_f32_16x16x32_bf16 v[82:85], v[144:147], v[208:211], v[82:85]
	s_setprio 0
	s_setprio 1
	v_mfma_f32_16x16x32_bf16 v[112:115], v[148:151], v[164:167], v[112:115]
	v_mfma_f32_16x16x32_bf16 v[108:111], v[156:159], v[164:167], v[108:111]
	v_mfma_f32_16x16x32_bf16 v[94:97], v[148:151], v[182:185], v[94:97]
	v_mfma_f32_16x16x32_bf16 v[90:93], v[156:159], v[182:185], v[90:93]
	v_mfma_f32_16x16x32_bf16 v[78:81], v[148:151], v[190:193], v[78:81]
	v_mfma_f32_16x16x32_bf16 v[74:77], v[156:159], v[190:193], v[74:77]
	v_mfma_f32_16x16x32_bf16 v[70:73], v[148:151], v[204:207], v[70:73]
	v_mfma_f32_16x16x32_bf16 v[66:69], v[156:159], v[204:207], v[66:69]
	v_mfma_f32_16x16x32_bf16 v[112:115], v[152:155], v[168:171], v[112:115]
	v_mfma_f32_16x16x32_bf16 v[108:111], v[160:163], v[168:171], v[108:111]
	v_mfma_f32_16x16x32_bf16 v[94:97], v[152:155], v[186:189], v[94:97]
	v_mfma_f32_16x16x32_bf16 v[90:93], v[160:163], v[186:189], v[90:93]
	v_mfma_f32_16x16x32_bf16 v[78:81], v[152:155], v[194:197], v[78:81]
	v_mfma_f32_16x16x32_bf16 v[74:77], v[160:163], v[194:197], v[74:77]
	v_mfma_f32_16x16x32_bf16 v[70:73], v[152:155], v[208:211], v[70:73]
	v_mfma_f32_16x16x32_bf16 v[66:69], v[160:163], v[208:211], v[66:69]
	s_setprio 0
	s_barrier
	s_add_i32 s50, s64, s2
	v_lshl_add_u64 v[214:215], v[214:215], 0, s[28:29]
	s_mov_b32 m0, s50
	ds_read_b128 v[164:167], v199 offset:49152
	ds_read_b128 v[168:171], v199 offset:50176
	ds_read_b128 v[182:185], v199 offset:51200
	ds_read_b128 v[186:189], v199 offset:52224
	ds_read_b128 v[190:193], v199 offset:53248
	ds_read_b128 v[194:197], v199 offset:54272
	ds_read_b128 v[204:207], v199 offset:55296
	ds_read_b128 v[208:211], v199 offset:56320
	s_setprio 1
	global_load_lds_dwordx4 v[214:215], off
	s_add_i32 m0, s50, 0x2000
	s_add_u32 s50, s54, 0xb0080
	v_lshl_add_u64 v[214:215], v[216:217], 0, s[28:29]
	s_addc_u32 s51, s55, 0
	s_add_i32 s54, s65, s2
	global_load_lds_dwordx4 v[214:215], off
	v_lshl_add_u64 v[214:215], s[50:51], 0, v[98:99]
	s_mov_b32 m0, s54
	s_nop 0
	global_load_lds_dwordx4 v[214:215], off
	v_lshl_add_u64 v[214:215], s[50:51], 0, v[172:173]
	s_add_i32 m0, s54, 0x2000
	s_nop 0
	global_load_lds_dwordx4 v[214:215], off
	v_lshl_add_u64 v[214:215], v[218:219], 0, s[28:29]
	s_mov_b32 m0, s12
	s_nop 0
	global_load_lds_dwordx4 v[214:215], off
	v_lshl_add_u64 v[214:215], v[220:221], 0, s[28:29]
	s_mov_b32 m0, s13
	s_nop 0
	global_load_lds_dwordx4 v[214:215], off
	s_waitcnt vmcnt(8)
	s_waitcnt lgkmcnt(0)
	s_barrier
	v_mfma_f32_16x16x32_bf16 v[62:65], v[132:135], v[164:167], v[62:65]
	v_mfma_f32_16x16x32_bf16 v[58:61], v[140:143], v[164:167], v[58:61]
	v_mfma_f32_16x16x32_bf16 v[54:57], v[132:135], v[182:185], v[54:57]
	v_mfma_f32_16x16x32_bf16 v[50:53], v[140:143], v[182:185], v[50:53]
	v_mfma_f32_16x16x32_bf16 v[38:41], v[132:135], v[190:193], v[38:41]
	v_mfma_f32_16x16x32_bf16 v[34:37], v[140:143], v[190:193], v[34:37]
	v_mfma_f32_16x16x32_bf16 v[22:25], v[132:135], v[204:207], v[22:25]
	v_mfma_f32_16x16x32_bf16 v[18:21], v[140:143], v[204:207], v[18:21]
	v_mfma_f32_16x16x32_bf16 v[62:65], v[136:139], v[168:171], v[62:65]
	v_mfma_f32_16x16x32_bf16 v[58:61], v[144:147], v[168:171], v[58:61]
	v_mfma_f32_16x16x32_bf16 v[54:57], v[136:139], v[186:189], v[54:57]
	v_mfma_f32_16x16x32_bf16 v[50:53], v[144:147], v[186:189], v[50:53]
	v_mfma_f32_16x16x32_bf16 v[38:41], v[136:139], v[194:197], v[38:41]
	v_mfma_f32_16x16x32_bf16 v[34:37], v[144:147], v[194:197], v[34:37]
	v_mfma_f32_16x16x32_bf16 v[22:25], v[136:139], v[208:211], v[22:25]
	v_mfma_f32_16x16x32_bf16 v[18:21], v[144:147], v[208:211], v[18:21]
	s_setprio 0
	s_setprio 1
	v_mfma_f32_16x16x32_bf16 v[46:49], v[148:151], v[164:167], v[46:49]
	v_mfma_f32_16x16x32_bf16 v[42:45], v[156:159], v[164:167], v[42:45]
	v_mfma_f32_16x16x32_bf16 v[30:33], v[148:151], v[182:185], v[30:33]
	v_mfma_f32_16x16x32_bf16 v[26:29], v[156:159], v[182:185], v[26:29]
	v_mfma_f32_16x16x32_bf16 v[14:17], v[148:151], v[190:193], v[14:17]
	v_mfma_f32_16x16x32_bf16 v[10:13], v[156:159], v[190:193], v[10:13]
	v_mfma_f32_16x16x32_bf16 v[6:9], v[148:151], v[204:207], v[6:9]
	v_mfma_f32_16x16x32_bf16 v[2:5], v[156:159], v[204:207], v[2:5]
	v_mfma_f32_16x16x32_bf16 v[46:49], v[152:155], v[168:171], v[46:49]
	v_mfma_f32_16x16x32_bf16 v[42:45], v[160:163], v[168:171], v[42:45]
	v_mfma_f32_16x16x32_bf16 v[30:33], v[152:155], v[186:189], v[30:33]
	v_mfma_f32_16x16x32_bf16 v[26:29], v[160:163], v[186:189], v[26:29]
	v_mfma_f32_16x16x32_bf16 v[14:17], v[152:155], v[194:197], v[14:17]
	v_mfma_f32_16x16x32_bf16 v[10:13], v[160:163], v[194:197], v[10:13]
	v_mfma_f32_16x16x32_bf16 v[6:9], v[152:155], v[208:211], v[6:9]
	v_mfma_f32_16x16x32_bf16 v[2:5], v[160:163], v[208:211], v[2:5]
	s_setprio 0
	s_barrier
	s_add_u32 s61, s61, 0x100
	s_addc_u32 s62, s62, 0
	s_cmp_ge_i32 s63, s59
	s_mov_b64 s[50:51], s[52:53]
	s_mov_b32 s54, s63
	s_cbranch_scc0 .LBB0_1553
	s_and_b64 vcc, exec, s[42:43]
	s_cbranch_vccz .LBB0_1556
	s_barrier
